# prompt attention K rows fetched row-contiguous (4 lanes per 64-B segment) and moved to fragment lanes with ds_bpermute; up-GEMM epilogue stores made row-contiguous the same way
# speedup vs baseline: 1.1242x; 1.0147x over previous
; __device__ __forceinline__ unsigned pk2(float lo, float hi) { const f32x2_t v = {lo, hi}; const bf16x2_t b = __builtin_convertvector(v, bf16x2_t); return __builtin_bit_cast(unsigned, b); }
; template <bool SAMPLE> ...
;     ...
;                 } else {
;                     int sk = s0 - 128 + 32 * kk + rl; sk = sk < 0 ? 0 : sk; sk = sk > s0 + 15 ? s0 + 15 : sk;
;                     w = *(const u32x4*)(Vb + ((size_t)b * SEQ + ((sk << dsh) + r)) * ATT + h * 64 + ch * 8);
;                 }
;                 vr[kk][it] = w;
;             }
;         }
;     }
;     f32x4 S[9];
; #pragma unroll
;     for (int kt = 0; kt < 9; ++kt) {
;         S[kt] = (f32x4){-1e30f, -1e30f, -1e30f, -1e30f};
;         if (kt >= kt0) {
;             bf16x8 k0, k1;
;             if (SAMPLE) {
;                 int j = 16 * kt + fr; j = j > 128 ? 128 : j;
;                 const int rr = npre + qi - (j << dsh);
;                 if (rr >= npre) { const bf16_t* kp = Kb + ((size_t)MP + b * 4 + (rr - npre)) * ATT + h * 64 + fq * 8; k0 = *(const bf16x8*)kp; k1 = *(const bf16x8*)(kp + 32); }
;                 else { const float* kp = cbase + (size_t)rr * 512 + hs * 64 + fq * 8;
;                     const f32x4 a0 = __builtin_nontemporal_load((const f32x4*)kp), a1 = __builtin_nontemporal_load((const f32x4*)(kp + 4)), a2 = __builtin_nontemporal_load((const f32x4*)(kp + 32)), a3 = __builtin_nontemporal_load((const f32x4*)(kp + 36));
;                     u32x4 w0, w1; w0.x = pk2(a0.x, a0.y); w0.y = pk2(a0.z, a0.w); w0.z = pk2(a1.x, a1.y); w0.w = pk2(a1.z, a1.w);
;                     w1.x = pk2(a2.x, a2.y); w1.y = pk2(a2.z, a2.w); w1.z = pk2(a3.x, a3.y); w1.w = pk2(a3.z, a3.w);
;                     k0 = __builtin_bit_cast(bf16x8, w0); k1 = __builtin_bit_cast(bf16x8, w1); }
;             } else {
;                 const int sk = s0 - 128 + 16 * kt + fr;
;                 const bf16_t* kp = Kb + ((size_t)b * SEQ + ((sk << dsh) + r)) * ATT + h * 64 + fq * 8;
;                 k0 = *(const bf16x8*)kp; k1 = *(const bf16x8*)(kp + 32);
;             }
;             f32x4 a = (f32x4){0.f, 0.f, 0.f, 0.f};
;             a = __builtin_amdgcn_mfma_f32_16x16x32_bf16(k0, q0, a, 0, 0, 0);
;             a = __builtin_amdgcn_mfma_f32_16x16x32_bf16(k1, q1, a, 0, 0, 0);
;             S[kt] = a;
;         }
.LBB0_1722:
	v_add_u32_e32 v48, s55, v133
	v_max_i32_e32 v48, 0, v48
	v_min_i32_e32 v48, s54, v48
	v_lshlrev_b32_e32 v48, s0, v48
	v_add_u32_e32 v48, s29, v48
	v_ashrrev_i32_e32 v49, 31, v48
	v_max_i32_e32 v76, 0xffffff70, v3
	v_lshl_add_u64 v[48:49], s[70:71], 0, v[48:49]
	v_add_u32_e32 v76, 0x90, v76
	v_mad_u64_u32 v[50:51], s[56:57], v48, s28, v[0:1]
	v_max_i32_e32 v48, 0xffffff78, v3
	v_min_u32_e32 v76, s54, v76
	v_add_u32_e32 v48, 0x88, v48
	v_lshlrev_b32_e32 v76, s0, v76
	v_max_i32_e32 v3, 0xffffff68, v3
	v_min_u32_e32 v48, s54, v48
	v_add_u32_e32 v76, s29, v76
	v_add_u32_e32 v3, 0x98, v3
	v_lshlrev_b32_e32 v48, s0, v48
	v_ashrrev_i32_e32 v77, 31, v76
	v_min_u32_e32 v3, s54, v3
	v_add_u32_e32 v48, s29, v48
	v_lshl_add_u64 v[76:77], s[70:71], 0, v[76:77]
	v_lshlrev_b32_e32 v3, s0, v3
	v_mad_i32_i24 v51, v49, s28, v51
	v_ashrrev_i32_e32 v49, 31, v48
	v_mad_u64_u32 v[78:79], s[56:57], v76, s28, v[0:1]
	v_add_u32_e32 v76, s29, v3
	v_lshl_add_u64 v[48:49], s[70:71], 0, v[48:49]
	v_mad_i32_i24 v79, v77, s28, v79
	v_ashrrev_i32_e32 v77, 31, v76
	v_mad_u64_u32 v[56:57], s[56:57], v48, s28, v[0:1]
	v_lshl_add_u64 v[76:77], s[70:71], 0, v[76:77]
	v_mad_i32_i24 v57, v49, s28, v57
	v_mad_u64_u32 v[0:1], s[54:55], v76, s28, v[0:1]
	global_load_dwordx4 v[48:51], v[50:51], off
	s_nop 0
	global_load_dwordx4 v[56:59], v[56:57], off
	v_mad_i32_i24 v1, v77, s28, v1
	global_load_dwordx4 v[76:79], v[78:79], off
	s_nop 0
	global_load_dwordx4 v[80:83], v[0:1], off
	v_lshl_add_u64 v[0:1], v[126:127], 0, s[4:5]
	v_or_b32_e32 v3, s30, v160
	v_lshrrev_b32_e32 v198, 2, v219
	v_add_u32_e32 v198, s30, v198
	v_and_b32_e32 v202, 3, v219
	v_lshrrev_b32_e32 v203, 4, v219
	v_sub_u32_e32 v202, v202, v203
	v_lshlrev_b32_e32 v202, 4, v202
	v_ashrrev_i32_e32 v203, 31, v202
	v_lshl_add_u64 v[200:201], v[202:203], 0, v[0:1]
	v_and_b32_e32 v199, 15, v219
	v_lshrrev_b32_e32 v202, 4, v219
	v_lshl_add_u32 v199, v199, 2, v202
	v_lshlrev_b32_e32 v199, 2, v199
	v_mov_b32_e32 v92, 0xf149f2ca
	s_cmp_lg_u32 s1, 0
	v_mov_b32_e32 v108, 0xf149f2ca
	v_mov_b32_e32 v109, 0xf149f2ca
	v_mov_b32_e32 v110, 0xf149f2ca
	v_mov_b32_e32 v111, 0xf149f2ca
	s_cbranch_scc1 .LBB0_1724
	v_add_u32_e32 v202, 0, v198
	v_lshlrev_b32_e32 v202, s0, v202
	v_add_u32_e32 v202, s29, v202
	v_ashrrev_i32_e32 v203, 31, v202
	v_lshl_add_u64 v[202:203], s[70:71], 0, v[202:203]
	v_mad_u64_u32 v[204:205], vcc, v202, s28, v[200:201]
	v_mad_i32_i24 v205, v203, s28, v205
	global_load_dwordx4 v[108:111], v[204:205], off
	global_load_dwordx4 v[182:185], v[204:205], off offset:64
.LBB0_1724:
	v_cndmask_b32_e64 v93, 0, 1, s[6:7]
	v_cmp_ne_u32_e64 s[58:59], 1, v93
	s_andn2_b64 vcc, exec, s[6:7]
	v_mov_b32_e32 v93, 0xf149f2ca
	s_nop 1
	v_mov_b32_e32 v94, 0xf149f2ca
	v_mov_b32_e32 v95, 0xf149f2ca
	s_cbranch_vccnz .LBB0_1726
	v_add_u32_e32 v202, 16, v198
	v_lshlrev_b32_e32 v202, s0, v202
	v_add_u32_e32 v202, s29, v202
	v_ashrrev_i32_e32 v203, 31, v202
	v_lshl_add_u64 v[202:203], s[70:71], 0, v[202:203]
	v_mad_u64_u32 v[204:205], vcc, v202, s28, v[200:201]
	v_mad_i32_i24 v205, v203, s28, v205
	global_load_dwordx4 v[92:95], v[204:205], off
	global_load_dwordx4 v[186:189], v[204:205], off offset:64
.LBB0_1726:
	v_mov_b32_e32 v96, 0xf149f2ca
	s_cmp_gt_u32 s1, 2
	v_mov_b32_e32 v100, 0xf149f2ca
	v_mov_b32_e32 v101, 0xf149f2ca
	v_mov_b32_e32 v102, 0xf149f2ca
	v_mov_b32_e32 v103, 0xf149f2ca
	s_cbranch_scc1 .LBB0_1728
	v_add_u32_e32 v202, 32, v198
	v_lshlrev_b32_e32 v202, s0, v202
	v_add_u32_e32 v202, s29, v202
	v_ashrrev_i32_e32 v203, 31, v202
	v_lshl_add_u64 v[202:203], s[70:71], 0, v[202:203]
	v_mad_u64_u32 v[204:205], vcc, v202, s28, v[200:201]
	v_mad_i32_i24 v205, v203, s28, v205
	global_load_dwordx4 v[100:103], v[204:205], off
	global_load_dwordx4 v[190:193], v[204:205], off offset:64
.LBB0_1728:
	v_cndmask_b32_e64 v97, 0, 1, s[52:53]
	v_cmp_ne_u32_e64 s[56:57], 1, v97
	s_andn2_b64 vcc, exec, s[52:53]
	v_mov_b32_e32 v97, 0xf149f2ca
	s_nop 1
	v_mov_b32_e32 v98, 0xf149f2ca
	v_mov_b32_e32 v99, 0xf149f2ca
	s_cbranch_vccnz .LBB0_1730
	v_add_u32_e32 v202, 48, v198
	v_lshlrev_b32_e32 v202, s0, v202
	v_add_u32_e32 v202, s29, v202
	v_ashrrev_i32_e32 v203, 31, v202
	v_lshl_add_u64 v[202:203], s[70:71], 0, v[202:203]
	v_mad_u64_u32 v[204:205], vcc, v202, s28, v[200:201]
	v_mad_i32_i24 v205, v203, s28, v205
	global_load_dwordx4 v[96:99], v[204:205], off
	global_load_dwordx4 v[194:197], v[204:205], off offset:64
.LBB0_1730:
	v_mov_b32_e32 v104, 0xf149f2ca
	s_cmp_gt_u32 s1, 4
	v_mov_b32_e32 v112, 0xf149f2ca
	v_mov_b32_e32 v113, 0xf149f2ca
	v_mov_b32_e32 v114, 0xf149f2ca
	v_mov_b32_e32 v115, 0xf149f2ca
	s_cbranch_scc1 .LBB0_1732
	v_add_u32_e32 v202, 64, v198
	v_lshlrev_b32_e32 v202, s0, v202
	v_add_u32_e32 v202, s29, v202
	v_ashrrev_i32_e32 v203, 31, v202
	v_lshl_add_u64 v[202:203], s[70:71], 0, v[202:203]
	v_mad_u64_u32 v[204:205], vcc, v202, s28, v[200:201]
	v_mad_i32_i24 v205, v203, s28, v205
	global_load_dwordx4 v[112:115], v[204:205], off
	global_load_dwordx4 v[206:209], v[204:205], off offset:64
.LBB0_1732:
	v_cndmask_b32_e64 v105, 0, 1, s[76:77]
	v_cmp_ne_u32_e64 s[54:55], 1, v105
	s_andn2_b64 vcc, exec, s[76:77]
	v_mov_b32_e32 v105, 0xf149f2ca
	v_mov_b32_e32 v106, 0xf149f2ca
	v_mov_b32_e32 v107, 0xf149f2ca
	s_cbranch_vccnz .LBB0_1734
	v_add_u32_e32 v202, 80, v198
	v_lshlrev_b32_e32 v202, s0, v202
	v_add_u32_e32 v202, s29, v202
	v_ashrrev_i32_e32 v203, 31, v202
	v_lshl_add_u64 v[202:203], s[70:71], 0, v[202:203]
	v_mad_u64_u32 v[204:205], vcc, v202, s28, v[200:201]
	v_mad_i32_i24 v205, v203, s28, v205
	global_load_dwordx4 v[104:107], v[204:205], off
	global_load_dwordx4 v[154:157], v[204:205], off offset:64
; __device__ __forceinline__ unsigned pk2(float lo, float hi) { const f32x2_t v = {lo, hi}; const bf16x2_t b = __builtin_convertvector(v, bf16x2_t); return __builtin_bit_cast(unsigned, b); }
; template <bool SAMPLE> ...
;     ...
;     for (int kt = 0; kt < 9; ++kt) {
;         S[kt] = (f32x4){-1e30f, -1e30f, -1e30f, -1e30f};
;         if (kt >= kt0) {
;             bf16x8 k0, k1;
;             if (SAMPLE) {
;                 int j = 16 * kt + fr; j = j > 128 ? 128 : j;
;                 const int rr = npre + qi - (j << dsh);
;                 if (rr >= npre) { const bf16_t* kp = Kb + ((size_t)MP + b * 4 + (rr - npre)) * ATT + h * 64 + fq * 8; k0 = *(const bf16x8*)kp; k1 = *(const bf16x8*)(kp + 32); }
;                 else { const float* kp = cbase + (size_t)rr * 512 + hs * 64 + fq * 8;
;                     const f32x4 a0 = __builtin_nontemporal_load((const f32x4*)kp), a1 = __builtin_nontemporal_load((const f32x4*)(kp + 4)), a2 = __builtin_nontemporal_load((const f32x4*)(kp + 32)), a3 = __builtin_nontemporal_load((const f32x4*)(kp + 36));
;                     u32x4 w0, w1; w0.x = pk2(a0.x, a0.y); w0.y = pk2(a0.z, a0.w); w0.z = pk2(a1.x, a1.y); w0.w = pk2(a1.z, a1.w);
;                     w1.x = pk2(a2.x, a2.y); w1.y = pk2(a2.z, a2.w); w1.z = pk2(a3.x, a3.y); w1.w = pk2(a3.z, a3.w);
;                     k0 = __builtin_bit_cast(bf16x8, w0); k1 = __builtin_bit_cast(bf16x8, w1); }
;             } else {
;                 const int sk = s0 - 128 + 16 * kt + fr;
;                 const bf16_t* kp = Kb + ((size_t)b * SEQ + ((sk << dsh) + r)) * ATT + h * 64 + fq * 8;
;                 k0 = *(const bf16x8*)kp; k1 = *(const bf16x8*)(kp + 32);
;             }
;             f32x4 a = (f32x4){0.f, 0.f, 0.f, 0.f};
;             a = __builtin_amdgcn_mfma_f32_16x16x32_bf16(k0, q0, a, 0, 0, 0);
;             a = __builtin_amdgcn_mfma_f32_16x16x32_bf16(k1, q1, a, 0, 0, 0);
;             S[kt] = a;
;         }
.LBB0_1734:
	v_mov_b32_e32 v116, 0xf149f2ca
	s_cmp_gt_u32 s1, 6
	v_mov_b32_e32 v120, 0xf149f2ca
	v_mov_b32_e32 v121, 0xf149f2ca
	v_mov_b32_e32 v122, 0xf149f2ca
	v_mov_b32_e32 v123, 0xf149f2ca
	s_mov_b32 s76, 0x30000
	s_cbranch_scc1 .LBB0_1736
	v_add_u32_e32 v202, 96, v198
	v_lshlrev_b32_e32 v202, s0, v202
	v_add_u32_e32 v202, s29, v202
	v_ashrrev_i32_e32 v203, 31, v202
	v_lshl_add_u64 v[202:203], s[70:71], 0, v[202:203]
	v_mad_u64_u32 v[204:205], vcc, v202, s28, v[200:201]
	v_mad_i32_i24 v205, v203, s28, v205
	global_load_dwordx4 v[120:123], v[204:205], off
	global_load_dwordx4 v[162:165], v[204:205], off offset:64
.LBB0_1736:
	v_cndmask_b32_e64 v117, 0, 1, s[78:79]
	v_cmp_ne_u32_e64 s[52:53], 1, v117
	s_andn2_b64 vcc, exec, s[78:79]
	v_mov_b32_e32 v117, 0xf149f2ca
	s_nop 1
	v_mov_b32_e32 v118, 0xf149f2ca
	v_mov_b32_e32 v119, 0xf149f2ca
	s_cbranch_vccnz .LBB0_1738
	v_add_u32_e32 v202, 112, v198
	v_lshlrev_b32_e32 v202, s0, v202
	v_add_u32_e32 v202, s29, v202
	v_ashrrev_i32_e32 v203, 31, v202
	v_lshl_add_u64 v[202:203], s[70:71], 0, v[202:203]
	v_mad_u64_u32 v[204:205], vcc, v202, s28, v[200:201]
	v_mad_i32_i24 v205, v203, s28, v205
	global_load_dwordx4 v[116:119], v[204:205], off
	global_load_dwordx4 v[166:169], v[204:205], off offset:64
.LBB0_1738:
	v_add_u32_e32 v146, 0x80, v198
	v_lshlrev_b32_e32 v146, s0, v146
	v_add_u32_e32 v146, s29, v146
	v_ashrrev_i32_e32 v147, 31, v146
	v_lshl_add_u64 v[146:147], s[70:71], 0, v[146:147]
	v_mad_u64_u32 v[204:205], vcc, v146, s28, v[200:201]
	v_mad_i32_i24 v205, v147, s28, v205
	global_load_dwordx4 v[146:149], v[204:205], off
	global_load_dwordx4 v[150:153], v[204:205], off offset:64
	s_waitcnt vmcnt(0)
	s_cmp_gt_u32 s1, 0
	s_cbranch_scc1 .Lpk2_ah_0
	ds_bpermute_b32 v108, v199, v108
	ds_bpermute_b32 v109, v199, v109
	ds_bpermute_b32 v110, v199, v110
	ds_bpermute_b32 v111, v199, v111
	ds_bpermute_b32 v182, v199, v182
	ds_bpermute_b32 v183, v199, v183
	ds_bpermute_b32 v184, v199, v184
	ds_bpermute_b32 v185, v199, v185
.Lpk2_ah_0:
	s_cmp_gt_u32 s1, 1
	s_cbranch_scc1 .Lpk2_ah_1
	ds_bpermute_b32 v92, v199, v92
	ds_bpermute_b32 v93, v199, v93
	ds_bpermute_b32 v94, v199, v94
	ds_bpermute_b32 v95, v199, v95
	ds_bpermute_b32 v186, v199, v186
	ds_bpermute_b32 v187, v199, v187
	ds_bpermute_b32 v188, v199, v188
	ds_bpermute_b32 v189, v199, v189
.Lpk2_ah_1:
	s_cmp_gt_u32 s1, 2
	s_cbranch_scc1 .Lpk2_ah_2
	ds_bpermute_b32 v100, v199, v100
	ds_bpermute_b32 v101, v199, v101
	ds_bpermute_b32 v102, v199, v102
	ds_bpermute_b32 v103, v199, v103
	ds_bpermute_b32 v190, v199, v190
	ds_bpermute_b32 v191, v199, v191
	ds_bpermute_b32 v192, v199, v192
	ds_bpermute_b32 v193, v199, v193
.Lpk2_ah_2:
	s_cmp_gt_u32 s1, 3
	s_cbranch_scc1 .Lpk2_ah_3
	ds_bpermute_b32 v96, v199, v96
	ds_bpermute_b32 v97, v199, v97
	ds_bpermute_b32 v98, v199, v98
	ds_bpermute_b32 v99, v199, v99
	ds_bpermute_b32 v194, v199, v194
	ds_bpermute_b32 v195, v199, v195
	ds_bpermute_b32 v196, v199, v196
	ds_bpermute_b32 v197, v199, v197
.Lpk2_ah_3:
	s_cmp_gt_u32 s1, 4
	s_cbranch_scc1 .Lpk2_ah_4
	ds_bpermute_b32 v112, v199, v112
	ds_bpermute_b32 v113, v199, v113
	ds_bpermute_b32 v114, v199, v114
	ds_bpermute_b32 v115, v199, v115
	ds_bpermute_b32 v206, v199, v206
	ds_bpermute_b32 v207, v199, v207
	ds_bpermute_b32 v208, v199, v208
	ds_bpermute_b32 v209, v199, v209
.Lpk2_ah_4:
	s_cmp_gt_u32 s1, 5
	s_cbranch_scc1 .Lpk2_ah_5
	ds_bpermute_b32 v104, v199, v104
	ds_bpermute_b32 v105, v199, v105
	ds_bpermute_b32 v106, v199, v106
	ds_bpermute_b32 v107, v199, v107
	ds_bpermute_b32 v154, v199, v154
	ds_bpermute_b32 v155, v199, v155
	ds_bpermute_b32 v156, v199, v156
	ds_bpermute_b32 v157, v199, v157
.Lpk2_ah_5:
	s_cmp_gt_u32 s1, 6
	s_cbranch_scc1 .Lpk2_ah_6
	ds_bpermute_b32 v120, v199, v120
	ds_bpermute_b32 v121, v199, v121
	ds_bpermute_b32 v122, v199, v122
	ds_bpermute_b32 v123, v199, v123
	ds_bpermute_b32 v162, v199, v162
	ds_bpermute_b32 v163, v199, v163
	ds_bpermute_b32 v164, v199, v164
	ds_bpermute_b32 v165, v199, v165
.Lpk2_ah_6:
	s_cmp_gt_u32 s1, 7
	s_cbranch_scc1 .Lpk2_ah_7
	ds_bpermute_b32 v116, v199, v116
	ds_bpermute_b32 v117, v199, v117
	ds_bpermute_b32 v118, v199, v118
	ds_bpermute_b32 v119, v199, v119
	ds_bpermute_b32 v166, v199, v166
	ds_bpermute_b32 v167, v199, v167
	ds_bpermute_b32 v168, v199, v168
	ds_bpermute_b32 v169, v199, v169
.Lpk2_ah_7:
	ds_bpermute_b32 v146, v199, v146
	ds_bpermute_b32 v147, v199, v147
	ds_bpermute_b32 v148, v199, v148
	ds_bpermute_b32 v149, v199, v149
	ds_bpermute_b32 v150, v199, v150
	ds_bpermute_b32 v151, v199, v151
	ds_bpermute_b32 v152, v199, v152
	ds_bpermute_b32 v153, v199, v153
	s_waitcnt lgkmcnt(0)
	s_cmp_gt_u32 s1, 0
	s_cbranch_scc1 .Lpk2_bh_0
	v_mfma_f32_16x16x32_bf16 v[108:111], v[108:111], v[88:91], 0
	v_mfma_f32_16x16x32_bf16 v[108:111], v[182:185], v[84:87], v[108:111]
.Lpk2_bh_0:
	s_cmp_gt_u32 s1, 1
	s_cbranch_scc1 .Lpk2_bh_1
	v_mfma_f32_16x16x32_bf16 v[92:95], v[92:95], v[88:91], 0
	v_mfma_f32_16x16x32_bf16 v[92:95], v[186:189], v[84:87], v[92:95]
.Lpk2_bh_1:
	s_cmp_gt_u32 s1, 2
	s_cbranch_scc1 .Lpk2_bh_2
	v_mfma_f32_16x16x32_bf16 v[100:103], v[100:103], v[88:91], 0
	v_mfma_f32_16x16x32_bf16 v[100:103], v[190:193], v[84:87], v[100:103]
.Lpk2_bh_2:
	s_cmp_gt_u32 s1, 3
	s_cbranch_scc1 .Lpk2_bh_3
	v_mfma_f32_16x16x32_bf16 v[96:99], v[96:99], v[88:91], 0
	v_mfma_f32_16x16x32_bf16 v[96:99], v[194:197], v[84:87], v[96:99]
.Lpk2_bh_3:
	s_cmp_gt_u32 s1, 4
	s_cbranch_scc1 .Lpk2_bh_4
	v_mfma_f32_16x16x32_bf16 v[112:115], v[112:115], v[88:91], 0
	v_mfma_f32_16x16x32_bf16 v[112:115], v[206:209], v[84:87], v[112:115]
.Lpk2_bh_4:
	s_cmp_gt_u32 s1, 5
	s_cbranch_scc1 .Lpk2_bh_5
	v_mfma_f32_16x16x32_bf16 v[104:107], v[104:107], v[88:91], 0
	v_mfma_f32_16x16x32_bf16 v[104:107], v[154:157], v[84:87], v[104:107]
; template <bool SAMPLE> ...
;     ...
;     if (SAMPLE) {
; #pragma unroll
;         for (int j = 0; j < 4; ++j) if (4 * fq + j > 0) S[8][j] = -1e30f;
;     } else {
; #pragma unroll
;         for (int j = 0; j < 4; ++j) { if (4 * fq + j < fr) S[0][j] = -1e30f; if (4 * fq + j > fr) S[8][j] = -1e30f; }
;     }
;     float m = -1e30f;
; #pragma unroll
;     for (int kt = 0; kt < 9; ++kt) m = fmaxf(m, fmaxf(fmaxf(S[kt].x, S[kt].y), fmaxf(S[kt].z, S[kt].w)));
;     m = fmaxf(m, __shfl_xor(m, 16)); m = fmaxf(m, __shfl_xor(m, 32));
;     float den = 0.f;
; #pragma unroll
;     for (int kt = 0; kt < 9; ++kt) { S[kt].x = __builtin_amdgcn_exp2f(S[kt].x - m); S[kt].y = __builtin_amdgcn_exp2f(S[kt].y - m); S[kt].z = __builtin_amdgcn_exp2f(S[kt].z - m); S[kt].w = __builtin_amdgcn_exp2f(S[kt].w - m); den += (S[kt].x + S[kt].y) + (S[kt].z + S[kt].w); }
;     den += __shfl_xor(den, 16); den += __shfl_xor(den, 32);
.Lpk2_bh_5:
	s_cmp_gt_u32 s1, 6
	s_cbranch_scc1 .Lpk2_bh_6
	v_mfma_f32_16x16x32_bf16 v[120:123], v[120:123], v[88:91], 0
	v_mfma_f32_16x16x32_bf16 v[120:123], v[162:165], v[84:87], v[120:123]
.Lpk2_bh_6:
	s_cmp_gt_u32 s1, 7
	s_cbranch_scc1 .Lpk2_bh_7
	v_mfma_f32_16x16x32_bf16 v[116:119], v[116:119], v[88:91], 0
	v_mfma_f32_16x16x32_bf16 v[116:119], v[166:169], v[84:87], v[116:119]
.Lpk2_bh_7:
	s_nop 7
	v_cndmask_b32_e64 v1, v108, v232, s[36:37]
	v_cndmask_b32_e64 v3, v109, v232, s[40:41]
	v_cndmask_b32_e64 v109, v110, v232, s[42:43]
	v_cndmask_b32_e64 v110, v111, v232, s[46:47]
	v_max_f32_e32 v108, v95, v95
	v_max_f32_e32 v111, v94, v94
	v_max_f32_e32 v154, v103, v103
	v_max_f32_e32 v155, v102, v102
	v_max_f32_e32 v156, v99, v99
	v_max_f32_e32 v157, v98, v98
	v_max_f32_e32 v158, v115, v115
	v_max_f32_e32 v159, v114, v114
	v_max_f32_e32 v162, v107, v107
	v_max_f32_e32 v163, v106, v106
	v_max_f32_e32 v168, v3, v3
	v_max_f32_e32 v169, v1, v1
	v_max_f32_e32 v180, v110, v110
	v_max_f32_e32 v181, v109, v109
	v_mov_b32_e32 v0, s31
	v_max_f32_e32 v108, v111, v108
	v_max_f32_e32 v111, v155, v154
	v_max_f32_e32 v154, v157, v156
	v_max_f32_e32 v155, v159, v158
	v_max_f32_e32 v156, v163, v162
	v_max_f32_e32 v159, v169, v168
	v_max_f32_e32 v162, v181, v180
	v_max_f32_e32 v164, v123, v123
	v_max_f32_e32 v165, v122, v122
	v_max3_f32 v108, v92, v93, v108
	v_max3_f32 v111, v100, v101, v111
	v_max3_f32 v159, v159, v162, s31
	v_max_f32_e32 v166, v119, v119
	v_max_f32_e32 v167, v118, v118
	v_max_f32_e32 v157, v165, v164
	v_max3_f32 v154, v96, v97, v154
	v_max3_f32 v155, v112, v113, v155
	v_max3_f32 v108, v159, v108, v111
	v_max_f32_e32 v158, v167, v166
	v_max3_f32 v156, v104, v105, v156
	v_max3_f32 v157, v120, v121, v157
	v_max3_f32 v108, v108, v154, v155
	v_max3_f32 v158, v116, v117, v158
	v_max3_f32 v108, v108, v156, v157
	s_mov_b32 s6, s5
	s_mov_b32 s7, s5
	s_mov_b32 s4, s5
	s_and_b64 vcc, exec, s[58:59]
	s_mov_b32 s79, 0x10000
	s_mov_b32 s78, 0x20000
	v_mfma_f32_16x16x32_bf16 v[88:91], v[146:149], v[88:91], 0
	v_mfma_f32_16x16x32_bf16 v[84:87], v[150:153], v[84:87], v[88:91]
	s_nop 7
	v_cndmask_b32_e64 v0, v84, v0, s[38:39]
	v_cndmask_b32_e64 v86, v86, v232, s[44:45]
	v_cndmask_b32_e64 v87, v87, v232, s[48:49]
	v_cndmask_b32_e64 v0, v0, v84, s[36:37]
	v_max_f32_e32 v84, v87, v87
	v_max_f32_e32 v88, v86, v86
	v_cndmask_b32_e64 v85, v232, v85, s[36:37]
	v_max_f32_e32 v84, v88, v84
	v_max3_f32 v84, v0, v85, v84
	v_max3_f32 v84, v108, v158, v84
	ds_bpermute_b32 v88, v130, v84
	s_waitcnt lgkmcnt(0)
	v_max_f32_e32 v88, v88, v88
	v_max_f32_e32 v84, v84, v88
	ds_bpermute_b32 v88, v131, v84
	s_waitcnt lgkmcnt(0)
	v_max_f32_e32 v88, v88, v88
	v_max_f32_e32 v108, v84, v88
	v_sub_f32_e32 v1, v1, v108
	v_sub_f32_e32 v3, v3, v108
	v_sub_f32_e32 v84, v109, v108
	v_sub_f32_e32 v88, v110, v108
	v_sub_f32_e32 v89, v92, v108
	v_sub_f32_e32 v90, v93, v108
	v_sub_f32_e32 v91, v94, v108
	v_sub_f32_e32 v92, v95, v108
	v_exp_f32_e32 v164, v1
	v_exp_f32_e32 v165, v3
	v_exp_f32_e32 v166, v84
	v_exp_f32_e32 v167, v88
	v_sub_f32_e32 v93, v100, v108
	v_sub_f32_e32 v94, v101, v108
	v_sub_f32_e32 v95, v102, v108
	v_sub_f32_e32 v100, v103, v108
	v_exp_f32_e32 v158, v89
	v_exp_f32_e32 v159, v90
	v_exp_f32_e32 v162, v91
	v_exp_f32_e32 v163, v92
	v_sub_f32_e32 v96, v96, v108
	v_sub_f32_e32 v97, v97, v108
	v_sub_f32_e32 v98, v98, v108
	v_sub_f32_e32 v99, v99, v108
	v_exp_f32_e32 v150, v93
	v_exp_f32_e32 v151, v94
	v_exp_f32_e32 v152, v95
	v_exp_f32_e32 v153, v100
	v_exp_f32_e32 v154, v96
	v_exp_f32_e32 v155, v97
	v_exp_f32_e32 v156, v98
	v_exp_f32_e32 v157, v99
	v_add_f32_e32 v1, v164, v165
	v_add_f32_e32 v3, v166, v167
	v_add_f32_e32 v84, v158, v159
	v_add_f32_e32 v88, v162, v163
	v_add_f32_e32 v1, v1, v3
	v_add_f32_e32 v89, v150, v151
	v_add_f32_e32 v90, v152, v153
	v_add_f32_e32 v3, v84, v88
	v_add_f32_e32 v1, 0, v1
	v_add_f32_e32 v91, v154, v155
	v_add_f32_e32 v92, v156, v157
	v_add_f32_e32 v84, v89, v90
	v_add_f32_e32 v1, v3, v1
	v_sub_f32_e32 v3, v104, v108
	v_sub_f32_e32 v101, v112, v108
	v_sub_f32_e32 v102, v113, v108
	v_sub_f32_e32 v103, v114, v108
	v_sub_f32_e32 v109, v115, v108
	v_add_f32_e32 v88, v91, v92
	v_add_f32_e32 v1, v84, v1
	v_exp_f32_e32 v146, v3
	v_sub_f32_e32 v3, v105, v108
	v_exp_f32_e32 v112, v101
	v_exp_f32_e32 v113, v102
	v_exp_f32_e32 v114, v103
	v_exp_f32_e32 v115, v109
	v_add_f32_e32 v1, v88, v1
	v_exp_f32_e32 v147, v3
	v_sub_f32_e32 v3, v106, v108
	v_sub_f32_e32 v88, v120, v108
	v_exp_f32_e32 v148, v3
	v_sub_f32_e32 v3, v107, v108
	v_exp_f32_e32 v103, v88
	v_sub_f32_e32 v88, v121, v108
	v_exp_f32_e32 v149, v3
	v_exp_f32_e32 v104, v88
	v_sub_f32_e32 v88, v122, v108
	v_exp_f32_e32 v105, v88
	v_sub_f32_e32 v88, v123, v108
	v_add_f32_e32 v93, v112, v113
	v_add_f32_e32 v94, v114, v115
	v_exp_f32_e32 v106, v88
	v_add_f32_e32 v3, v93, v94
	v_sub_f32_e32 v88, v116, v108
	v_add_f32_e32 v1, v3, v1
	v_add_f32_e32 v3, v146, v147
	v_add_f32_e32 v84, v148, v149
	v_exp_f32_e32 v107, v88
	v_sub_f32_e32 v88, v117, v108
	v_add_f32_e32 v3, v3, v84
	v_exp_f32_e32 v109, v88
	v_sub_f32_e32 v88, v118, v108
	v_add_f32_e32 v1, v3, v1
	v_add_f32_e32 v3, v103, v104
	v_add_f32_e32 v84, v105, v106
	v_exp_f32_e32 v110, v88
	v_sub_f32_e32 v88, v119, v108
	v_exp_f32_e32 v111, v88
	v_add_f32_e32 v3, v3, v84
	v_add_f32_e32 v84, v3, v1
	v_sub_f32_e32 v0, v0, v108
	v_sub_f32_e32 v1, v85, v108
	v_sub_f32_e32 v3, v86, v108
	v_sub_f32_e32 v85, v87, v108
	v_exp_f32_e32 v0, v0
	v_exp_f32_e32 v1, v1
	v_exp_f32_e32 v3, v3
	v_exp_f32_e32 v102, v85
	v_add_f32_e32 v88, v107, v109
	v_add_f32_e32 v89, v110, v111
	v_add_f32_e32 v85, v88, v89
	v_add_f32_e32 v84, v85, v84
	v_add_f32_e32 v85, v0, v1
	v_add_f32_e32 v86, v3, v102
	v_add_f32_e32 v85, v85, v86
	v_add_f32_e32 v88, v85, v84
	ds_bpermute_b32 v89, v130, v88
	v_mov_b64_e32 v[86:87], s[6:7]
	v_mov_b64_e32 v[94:95], s[6:7]
	v_mov_b64_e32 v[98:99], s[6:7]
	v_mov_b64_e32 v[84:85], s[4:5]
	s_waitcnt lgkmcnt(0)
	v_add_f32_e32 v100, v88, v89
	ds_bpermute_b32 v101, v131, v100
	v_mov_b64_e32 v[90:91], s[6:7]
	v_mov_b64_e32 v[88:89], s[4:5]
	v_mov_b64_e32 v[92:93], s[4:5]
	v_mov_b64_e32 v[96:97], s[4:5]
	s_cbranch_vccz .LBB0_1745
	s_and_b64 vcc, exec, s[56:57]
	s_cbranch_vccz .LBB0_1746

; __device__ __forceinline__ void stats_main(const float* stm, int row, int fq, float& mu, float& rs) {
;     const f32x4* p = (const f32x4*)(stm + (size_t)row * 32 + fq * 8);
;     const f32x4 a = p[0], b = p[1];
;     float s1 = (a.x + a.z) + (b.x + b.z), s2 = (a.y + a.w) + (b.y + b.w);
;     s1 += __shfl_xor(s1, 16); s2 += __shfl_xor(s2, 16); s1 += __shfl_xor(s1, 32); s2 += __shfl_xor(s2, 32);
;     mu = s1 * (1.f / DM); rs = __builtin_amdgcn_rsqf(fmaxf(s2 * (1.f / DM) - mu * mu, 0.f) + LN_EPS);
; }
;     __device__ __forceinline__ void operator()(const f32x4 (&acc)[2][2][4][2], const pg8::Unit& u, int wr, int wc, int fr, int fq) const {
;         float mu[2][4], rs[2][4], ps1[2][4], ps2[2][4];
; #pragma unroll
;         for (int ai = 0; ai < 2; ++ai)
; #pragma unroll
;             for (int m = 0; m < 4; ++m) { ps1[ai][m] = 0.f; ps2[ai][m] = 0.f; mu[ai][m] = 0.f; rs[ai][m] = 1.f; if (fold) stats_main(stm, u.pm * 256 + ai * 128 + wr * 64 + m * 16 + fr, fq, mu[ai][m], rs[ai][m]); }
; #pragma unroll
;         for (int bj = 0; bj < 2; ++bj)
; #pragma unroll
;             for (int n = 0; n < 2; ++n) {
;                 const int col = u.pn * 256 + bj * 128 + wc * 32 + n * 16 + fq * 4;
;                 f32x4 c1v = (f32x4){0.f, 0.f, 0.f, 0.f}, c2v = c1v;
;                 if (fold) { c1v = *(const f32x4*)(c1 + col); c2v = *(const f32x4*)(c2 + col); }
.LBB0_2299:
	v_and_b32_e32 v238, 0xfffffff0, v155
	v_lshl_add_u32 v238, s22, 8, v238
	v_and_b32_e32 v239, 31, v219
	v_add_u32_e32 v238, v238, v239
	v_lshrrev_b32_e32 v239, 5, v219
	v_lshl_add_u32 v238, v239, 7, v238
	v_lshlrev_b32_e32 v238, 2, v238
	global_load_dword v242, v238, s[42:43]
	global_load_dword v243, v238, s[46:47]
	v_lshl_add_u32 v238, s23, 8, v3
	v_lshlrev_b32_e32 v246, 7, v238
	v_mov_b32_e32 v247, 0
	v_lshlrev_b32_e32 v248, 7, v238
	v_mov_b32_e32 v249, 0
	v_add_u32_e32 v246, 0x1000, v246
	v_add_u32_e32 v248, 0x5000, v248
	v_lshl_add_u64 v[246:247], v[246:247], 0, v[142:143]
	v_lshl_add_u64 v[248:249], v[248:249], 0, v[142:143]
	global_load_dwordx4 v[214:217], v[246:247], off offset:-4080
	global_load_dwordx4 v[234:237], v[246:247], off offset:-4096
	v_lshrrev_b32_e32 v238, 6, v3
	v_lshrrev_b32_e32 v239, 5, v155
	v_lshl_add_u32 v238, v238, 2, v239
	v_lshlrev_b32_e32 v238, 9, v238
	v_and_b32_e32 v239, 12, v155
	v_lshl_add_u32 v255, v239, 2, v238
	v_add_u32_e32 v255, 0x20000, v255
	v_lshl_add_u32 v238, v219, 2, v238
	v_add_u32_e32 v238, 0x20000, v238
	s_waitcnt vmcnt(3)
	ds_write_b32 v238, v242
	s_waitcnt vmcnt(2)
	ds_write_b32 v238, v243 offset:256
	global_load_dwordx4 v[238:241], v[246:247], off offset:-2032
	global_load_dwordx4 v[242:245], v[246:247], off offset:-2048
	s_waitcnt lgkmcnt(0)
	v_lshl_add_u32 v192, s23, 8, v3
	v_ashrrev_i32_e32 v193, 31, v192
	v_lshlrev_b64 v[132:133], 7, v[192:193]
	v_lshl_add_u64 v[136:137], v[142:143], 0, v[132:133]
	s_waitcnt vmcnt(3)
	v_mov_b64_e32 v[132:133], v[214:215]
	v_mov_b64_e32 v[134:135], v[216:217]
	global_load_dwordx4 v[214:217], v[246:247], off offset:16
	s_nop 0
	s_waitcnt vmcnt(3)
	v_mov_b64_e32 v[136:137], v[234:235]
	v_mov_b64_e32 v[138:139], v[236:237]
	global_load_dwordx4 v[234:237], v[246:247], off
	v_and_b32_e32 v149, 64, v219
	v_xor_b32_e32 v148, 16, v219
	v_add_u32_e32 v149, 64, v149
	v_cmp_lt_i32_e32 vcc, v148, v149
	v_or_b32_e32 v194, 16, v192
	v_ashrrev_i32_e32 v195, 31, v194
	v_cndmask_b32_e32 v148, v219, v148, vcc
	v_lshlrev_b32_e32 v160, 2, v148
	v_xor_b32_e32 v148, 32, v219
	v_cmp_lt_i32_e32 vcc, v148, v149
	v_or_b32_e32 v196, 32, v192
	v_ashrrev_i32_e32 v197, 31, v196
	v_cndmask_b32_e32 v148, v219, v148, vcc
	v_lshlrev_b32_e32 v161, 2, v148
	v_or_b32_e32 v204, 48, v192
	v_ashrrev_i32_e32 v205, 31, v204
	v_add_u32_e32 v206, 0x80, v192
	v_ashrrev_i32_e32 v207, 31, v206
	v_add_u32_e32 v202, 0x90, v192
	v_ashrrev_i32_e32 v203, 31, v202
	v_add_u32_e32 v200, 0xa0, v192
	v_ashrrev_i32_e32 v201, 31, v200
	v_add_u32_e32 v198, 0xb0, v192
	v_ashrrev_i32_e32 v199, 31, v198
	v_lshl_add_u32 v208, s22, 8, v155
	v_ashrrev_i32_e32 v209, 31, v208
	v_readlane_b32 s0, v254, 42
	v_readlane_b32 s1, v254, 43
	v_readlane_b32 s24, v251, 0
	s_andn2_b64 vcc, exec, s[40:41]
	v_readlane_b32 s25, v251, 1
	v_readlane_b32 s26, v251, 2
	v_readlane_b32 s27, v251, 3
	s_waitcnt lgkmcnt(0)
	v_pk_add_f32 v[132:133], v[132:133], v[134:135]
	v_pk_add_f32 v[136:137], v[136:137], v[138:139]
	s_nop 0
	v_pk_add_f32 v[132:133], v[136:137], v[132:133]
	ds_bpermute_b32 v134, v160, v132
	ds_bpermute_b32 v135, v160, v133
	s_waitcnt lgkmcnt(0)
	v_pk_add_f32 v[132:133], v[132:133], v[134:135]
	ds_bpermute_b32 v134, v161, v132
	ds_bpermute_b32 v135, v161, v133
	s_waitcnt lgkmcnt(0)
	v_pk_add_f32 v[132:133], v[132:133], v[134:135]
	s_nop 0
	v_pk_mul_f32 v[148:149], v[132:133], s[82:83] op_sel_hi:[1,0]
	s_nop 0
	v_fma_f32 v132, -v148, v148, v149
	v_max_f32_e32 v132, 0, v132
	v_add_f32_e32 v132, 0x3727c5ac, v132
	v_rsq_f32_e32 v150, v132
	v_lshlrev_b64 v[132:133], 7, v[194:195]
	v_lshl_add_u64 v[136:137], v[142:143], 0, v[132:133]
	s_waitcnt vmcnt(3)
	v_mov_b64_e32 v[132:133], v[238:239]
	v_mov_b64_e32 v[134:135], v[240:241]
	global_load_dwordx4 v[238:241], v[246:247], off offset:2064
	s_nop 0
	s_waitcnt vmcnt(3)
	v_mov_b64_e32 v[136:137], v[242:243]
	v_mov_b64_e32 v[138:139], v[244:245]
	global_load_dwordx4 v[242:245], v[246:247], off offset:2048
	s_waitcnt lgkmcnt(0)
	v_pk_add_f32 v[132:133], v[132:133], v[134:135]
	s_waitcnt lgkmcnt(0)
	v_pk_add_f32 v[136:137], v[136:137], v[138:139]
	s_nop 0
	v_pk_add_f32 v[132:133], v[136:137], v[132:133]
	ds_bpermute_b32 v134, v160, v132
	ds_bpermute_b32 v135, v160, v133
	s_waitcnt lgkmcnt(0)
	v_pk_add_f32 v[132:133], v[132:133], v[134:135]
	ds_bpermute_b32 v134, v161, v132
	ds_bpermute_b32 v135, v161, v133
	s_waitcnt lgkmcnt(0)
	v_pk_add_f32 v[132:133], v[132:133], v[134:135]
	s_nop 0
	v_pk_mul_f32 v[152:153], v[132:133], s[82:83] op_sel_hi:[1,0]
	s_nop 0
	v_fma_f32 v132, -v152, v152, v153
	v_max_f32_e32 v132, 0, v132
	v_add_f32_e32 v132, 0x3727c5ac, v132
	v_rsq_f32_e32 v154, v132
	v_lshlrev_b64 v[132:133], 7, v[196:197]
	v_lshl_add_u64 v[136:137], v[142:143], 0, v[132:133]
	s_waitcnt vmcnt(3)
	v_mov_b64_e32 v[132:133], v[214:215]
	v_mov_b64_e32 v[134:135], v[216:217]
	global_load_dwordx4 v[214:217], v[248:249], off offset:-4080
	s_nop 0
	s_waitcnt vmcnt(3)
	v_mov_b64_e32 v[136:137], v[234:235]
	v_mov_b64_e32 v[138:139], v[236:237]
	global_load_dwordx4 v[234:237], v[248:249], off offset:-4096
	s_waitcnt lgkmcnt(0)
	v_pk_add_f32 v[132:133], v[132:133], v[134:135]
	s_waitcnt lgkmcnt(0)
	v_pk_add_f32 v[136:137], v[136:137], v[138:139]
	s_nop 0
	v_pk_add_f32 v[132:133], v[136:137], v[132:133]
	ds_bpermute_b32 v134, v160, v132
	ds_bpermute_b32 v135, v160, v133
	s_waitcnt lgkmcnt(0)
	v_pk_add_f32 v[132:133], v[132:133], v[134:135]
	ds_bpermute_b32 v134, v161, v132
	ds_bpermute_b32 v135, v161, v133
	s_waitcnt lgkmcnt(0)
; __device__ __forceinline__ void stats_main(const float* stm, int row, int fq, float& mu, float& rs) {
;     const f32x4* p = (const f32x4*)(stm + (size_t)row * 32 + fq * 8);
;     const f32x4 a = p[0], b = p[1];
;     float s1 = (a.x + a.z) + (b.x + b.z), s2 = (a.y + a.w) + (b.y + b.w);
;     s1 += __shfl_xor(s1, 16); s2 += __shfl_xor(s2, 16); s1 += __shfl_xor(s1, 32); s2 += __shfl_xor(s2, 32);
;     mu = s1 * (1.f / DM); rs = __builtin_amdgcn_rsqf(fmaxf(s2 * (1.f / DM) - mu * mu, 0.f) + LN_EPS);
; }
;     __device__ __forceinline__ void operator()(const f32x4 (&acc)[2][2][4][2], const pg8::Unit& u, int wr, int wc, int fr, int fq) const {
;     ...
;             for (int m = 0; m < 4; ++m) { ps1[ai][m] = 0.f; ps2[ai][m] = 0.f; mu[ai][m] = 0.f; rs[ai][m] = 1.f; if (fold) stats_main(stm, u.pm * 256 + ai * 128 + wr * 64 + m * 16 + fr, fq, mu[ai][m], rs[ai][m]); }
; #pragma unroll
;         for (int bj = 0; bj < 2; ++bj)
; #pragma unroll
;             for (int n = 0; n < 2; ++n) {
;                 const int col = u.pn * 256 + bj * 128 + wc * 32 + n * 16 + fq * 4;
;                 f32x4 c1v = (f32x4){0.f, 0.f, 0.f, 0.f}, c2v = c1v;
;                 if (fold) { c1v = *(const f32x4*)(c1 + col); c2v = *(const f32x4*)(c2 + col); }
	v_pk_add_f32 v[132:133], v[132:133], v[134:135]
	s_nop 0
	v_pk_mul_f32 v[156:157], v[132:133], s[82:83] op_sel_hi:[1,0]
	s_nop 0
	v_fma_f32 v132, -v156, v156, v157
	v_max_f32_e32 v132, 0, v132
	v_add_f32_e32 v132, 0x3727c5ac, v132
	v_rsq_f32_e32 v158, v132
	v_lshlrev_b64 v[132:133], 7, v[204:205]
	v_lshl_add_u64 v[136:137], v[142:143], 0, v[132:133]
	s_waitcnt vmcnt(3)
	v_mov_b64_e32 v[132:133], v[238:239]
	v_mov_b64_e32 v[134:135], v[240:241]
	global_load_dwordx4 v[238:241], v[248:249], off offset:-2032
	s_nop 0
	s_waitcnt vmcnt(3)
	v_mov_b64_e32 v[136:137], v[242:243]
	v_mov_b64_e32 v[138:139], v[244:245]
	global_load_dwordx4 v[242:245], v[248:249], off offset:-2048
	s_waitcnt lgkmcnt(0)
	v_pk_add_f32 v[132:133], v[132:133], v[134:135]
	s_waitcnt lgkmcnt(0)
	v_pk_add_f32 v[136:137], v[136:137], v[138:139]
	s_nop 0
	v_pk_add_f32 v[132:133], v[136:137], v[132:133]
	ds_bpermute_b32 v134, v160, v132
	ds_bpermute_b32 v135, v160, v133
	s_waitcnt lgkmcnt(0)
	v_pk_add_f32 v[132:133], v[132:133], v[134:135]
	ds_bpermute_b32 v134, v161, v132
	ds_bpermute_b32 v135, v161, v133
	s_waitcnt lgkmcnt(0)
	v_pk_add_f32 v[132:133], v[132:133], v[134:135]
	s_nop 0
	v_pk_mul_f32 v[184:185], v[132:133], s[82:83] op_sel_hi:[1,0]
	s_nop 0
	v_fma_f32 v132, -v184, v184, v185
	v_max_f32_e32 v132, 0, v132
	v_add_f32_e32 v132, 0x3727c5ac, v132
	v_rsq_f32_e32 v190, v132
	v_lshlrev_b64 v[132:133], 7, v[206:207]
	v_lshl_add_u64 v[136:137], v[142:143], 0, v[132:133]
	s_waitcnt vmcnt(3)
	v_mov_b64_e32 v[132:133], v[214:215]
	v_mov_b64_e32 v[134:135], v[216:217]
	global_load_dwordx4 v[214:217], v[248:249], off offset:16
	s_nop 0
	s_waitcnt vmcnt(3)
	v_mov_b64_e32 v[136:137], v[234:235]
	v_mov_b64_e32 v[138:139], v[236:237]
	global_load_dwordx4 v[234:237], v[248:249], off
	s_waitcnt lgkmcnt(0)
	v_pk_add_f32 v[132:133], v[132:133], v[134:135]
	s_waitcnt lgkmcnt(0)
	v_pk_add_f32 v[136:137], v[136:137], v[138:139]
	s_nop 0
	v_pk_add_f32 v[132:133], v[136:137], v[132:133]
	ds_bpermute_b32 v134, v160, v132
	ds_bpermute_b32 v135, v160, v133
	s_waitcnt lgkmcnt(0)
	v_pk_add_f32 v[132:133], v[132:133], v[134:135]
	ds_bpermute_b32 v134, v161, v132
	ds_bpermute_b32 v135, v161, v133
	s_waitcnt lgkmcnt(0)
	v_pk_add_f32 v[132:133], v[132:133], v[134:135]
	s_nop 0
	v_pk_mul_f32 v[180:181], v[132:133], s[82:83] op_sel_hi:[1,0]
	s_nop 0
	v_fma_f32 v132, -v180, v180, v181
	v_max_f32_e32 v132, 0, v132
	v_add_f32_e32 v132, 0x3727c5ac, v132
	v_rsq_f32_e32 v188, v132
	v_lshlrev_b64 v[132:133], 7, v[202:203]
	v_lshl_add_u64 v[136:137], v[142:143], 0, v[132:133]
	s_waitcnt vmcnt(3)
	v_mov_b64_e32 v[132:133], v[238:239]
	v_mov_b64_e32 v[134:135], v[240:241]
	global_load_dwordx4 v[238:241], v[248:249], off offset:2064
	s_nop 0
	s_waitcnt vmcnt(3)
	v_mov_b64_e32 v[136:137], v[242:243]
	v_mov_b64_e32 v[138:139], v[244:245]
	global_load_dwordx4 v[242:245], v[248:249], off offset:2048
	s_waitcnt lgkmcnt(0)
	v_pk_add_f32 v[132:133], v[132:133], v[134:135]
	s_waitcnt lgkmcnt(0)
	v_pk_add_f32 v[136:137], v[136:137], v[138:139]
	s_nop 0
	v_pk_add_f32 v[132:133], v[136:137], v[132:133]
	ds_bpermute_b32 v134, v160, v132
	ds_bpermute_b32 v135, v160, v133
	s_waitcnt lgkmcnt(0)
	v_pk_add_f32 v[132:133], v[132:133], v[134:135]
	ds_bpermute_b32 v134, v161, v132
	ds_bpermute_b32 v135, v161, v133
	s_waitcnt lgkmcnt(0)
	v_pk_add_f32 v[132:133], v[132:133], v[134:135]
	s_nop 0
	v_pk_mul_f32 v[164:165], v[132:133], s[82:83] op_sel_hi:[1,0]
	s_nop 0
	v_fma_f32 v132, -v164, v164, v165
	v_max_f32_e32 v132, 0, v132
	v_add_f32_e32 v132, 0x3727c5ac, v132
	v_rsq_f32_e32 v186, v132
	v_lshlrev_b64 v[132:133], 7, v[200:201]
	v_lshl_add_u64 v[136:137], v[142:143], 0, v[132:133]
	s_waitcnt vmcnt(3)
	v_mov_b64_e32 v[132:133], v[214:215]
	v_mov_b64_e32 v[134:135], v[216:217]
	s_nop 0
	s_waitcnt vmcnt(2)
	v_mov_b64_e32 v[136:137], v[234:235]
	v_mov_b64_e32 v[138:139], v[236:237]
	s_waitcnt lgkmcnt(0)
	v_pk_add_f32 v[132:133], v[132:133], v[134:135]
	s_waitcnt lgkmcnt(0)
	v_pk_add_f32 v[136:137], v[136:137], v[138:139]
	s_nop 0
	v_pk_add_f32 v[132:133], v[136:137], v[132:133]
	ds_bpermute_b32 v134, v160, v132
	ds_bpermute_b32 v135, v160, v133
	s_waitcnt lgkmcnt(0)
	v_pk_add_f32 v[132:133], v[132:133], v[134:135]
	ds_bpermute_b32 v134, v161, v132
	ds_bpermute_b32 v135, v161, v133
	s_waitcnt lgkmcnt(0)
	v_pk_add_f32 v[132:133], v[132:133], v[134:135]
	s_nop 0
	v_pk_mul_f32 v[162:163], v[132:133], s[82:83] op_sel_hi:[1,0]
	s_nop 0
	v_fma_f32 v132, -v162, v162, v163
	v_max_f32_e32 v132, 0, v132
	v_add_f32_e32 v132, 0x3727c5ac, v132
	v_rsq_f32_e32 v182, v132
	v_lshlrev_b64 v[132:133], 7, v[198:199]
	v_lshl_add_u64 v[136:137], v[142:143], 0, v[132:133]
	s_waitcnt vmcnt(1)
	v_mov_b64_e32 v[132:133], v[238:239]
	v_mov_b64_e32 v[134:135], v[240:241]
	s_nop 0
	s_waitcnt vmcnt(0)
	v_mov_b64_e32 v[136:137], v[242:243]
	v_mov_b64_e32 v[138:139], v[244:245]
	s_waitcnt lgkmcnt(0)
	v_pk_add_f32 v[132:133], v[132:133], v[134:135]
	s_waitcnt lgkmcnt(0)
	v_pk_add_f32 v[136:137], v[136:137], v[138:139]
	s_nop 0
	v_pk_add_f32 v[132:133], v[136:137], v[132:133]
	ds_bpermute_b32 v134, v160, v132
	ds_bpermute_b32 v135, v160, v133
	v_lshlrev_b64 v[136:137], 2, v[208:209]
	s_waitcnt lgkmcnt(0)
	v_pk_add_f32 v[132:133], v[132:133], v[134:135]
	ds_bpermute_b32 v134, v161, v132
	ds_bpermute_b32 v135, v161, v133
	s_waitcnt lgkmcnt(0)
	v_pk_add_f32 v[132:133], v[132:133], v[134:135]
	s_nop 0
	v_pk_mul_f32 v[160:161], v[132:133], s[82:83] op_sel_hi:[1,0]
	s_nop 0
	v_fma_f32 v132, -v160, v160, v161
	v_max_f32_e32 v132, 0, v132
	v_add_f32_e32 v132, 0x3727c5ac, v132
	v_rsq_f32_e32 v166, v132
	v_lshl_add_u64 v[132:133], s[42:43], 0, v[136:137]
	ds_read_b128 v[132:135], v255
	v_lshl_add_u64 v[136:137], s[46:47], 0, v[136:137]
	ds_read_b128 v[136:139], v255 offset:256
	s_waitcnt lgkmcnt(0)
; __device__ __forceinline__ u32x2 pk4(f32x4 v) { u32x2 r; r.x = pk2(v.x, v.y); r.y = pk2(v.z, v.w); return r; }
;     __device__ __forceinline__ void operator()(int row, int col, f32x4 v, int, float&, float&) const { *(u32x2*)(O + (size_t)row * ldc + col) = pk4(v * s); }
;     __device__ __forceinline__ void operator()(const f32x4 (&acc)[2][2][4][2], const pg8::Unit& u, int wr, int wc, int fr, int fq) const {
;     ...
; #pragma unroll
;                 for (int ai = 0; ai < 2; ++ai)
; #pragma unroll
;                     for (int m = 0; m < 4; ++m) {
;                         f32x4 v = acc[ai][bj][m][n];
;                         if (fold) v = (v - c1v * mu[ai][m]) * rs[ai][m] + c2v;
;                         f(u.pm * 256 + ai * 128 + wr * 64 + m * 16 + fr, col, v, fq, ps1[ai][m], ps2[ai][m]);
;                     }
;     __device__ __forceinline__ void operator()(int row, int col, f32x4 v, int, float&, float&) const {
;         f32x4 r; r.x = fmaxf(v.x, 0.f); r.y = fmaxf(v.y, 0.f); r.z = fmaxf(v.z, 0.f); r.w = fmaxf(v.w, 0.f);
;         *(u32x2*)(O + (size_t)row * FF + col) = pk4(r * r);
;     }
	v_pk_fma_f32 v[128:129], v[148:149], v[132:133], v[128:129] op_sel_hi:[0,1,1] neg_lo:[1,0,0] neg_hi:[1,0,0]
	v_pk_fma_f32 v[130:131], v[148:149], v[134:135], v[130:131] op_sel_hi:[0,1,1] neg_lo:[1,0,0] neg_hi:[1,0,0]
	s_waitcnt lgkmcnt(0)
	v_pk_fma_f32 v[128:129], v[150:151], v[128:129], v[136:137] op_sel_hi:[0,1,1]
	v_pk_fma_f32 v[130:131], v[150:151], v[130:131], v[138:139] op_sel_hi:[0,1,1]
	v_max_f32_e32 v128, 0, v128
	v_max_f32_e32 v129, 0, v129
	v_max_f32_e32 v130, 0, v130
	v_max_f32_e32 v131, 0, v131
	v_pk_mul_f32 v[128:129], v[128:129], v[128:129]
	v_pk_fma_f32 v[126:127], v[152:153], v[134:135], v[126:127] op_sel_hi:[0,1,1] neg_lo:[1,0,0] neg_hi:[1,0,0]
	v_pk_fma_f32 v[122:123], v[156:157], v[134:135], v[122:123] op_sel_hi:[0,1,1] neg_lo:[1,0,0] neg_hi:[1,0,0]
	v_pk_fma_f32 v[118:119], v[184:185], v[134:135], v[118:119] op_sel_hi:[0,1,1] neg_lo:[1,0,0] neg_hi:[1,0,0]
	v_pk_fma_f32 v[114:115], v[180:181], v[134:135], v[114:115] op_sel_hi:[0,1,1] neg_lo:[1,0,0] neg_hi:[1,0,0]
	v_pk_fma_f32 v[110:111], v[164:165], v[134:135], v[110:111] op_sel_hi:[0,1,1] neg_lo:[1,0,0] neg_hi:[1,0,0]
	v_pk_fma_f32 v[102:103], v[162:163], v[134:135], v[102:103] op_sel_hi:[0,1,1] neg_lo:[1,0,0] neg_hi:[1,0,0]
	v_pk_mul_f32 v[130:131], v[130:131], v[130:131]
	v_cvt_pk_bf16_f32 v168, v128, v129
	v_lshlrev_b64 v[128:129], 13, v[192:193]
	v_pk_fma_f32 v[126:127], v[154:155], v[126:127], v[138:139] op_sel_hi:[0,1,1]
	v_pk_fma_f32 v[122:123], v[158:159], v[122:123], v[138:139] op_sel_hi:[0,1,1]
	v_pk_fma_f32 v[118:119], v[190:191], v[118:119], v[138:139] op_sel_hi:[0,1,1]
	v_pk_fma_f32 v[114:115], v[188:189], v[114:115], v[138:139] op_sel_hi:[0,1,1]
	v_pk_fma_f32 v[110:111], v[186:187], v[110:111], v[138:139] op_sel_hi:[0,1,1]
	v_pk_fma_f32 v[102:103], v[182:183], v[102:103], v[138:139] op_sel_hi:[0,1,1]
	v_cvt_pk_bf16_f32 v169, v130, v131
	v_lshl_add_u64 v[128:129], s[0:1], 0, v[128:129]
	v_lshlrev_b64 v[130:131], 1, v[208:209]
	v_max_f32_e32 v126, 0, v126
	v_max_f32_e32 v127, 0, v127
	v_max_f32_e32 v122, 0, v122
	v_max_f32_e32 v123, 0, v123
	v_max_f32_e32 v118, 0, v118
	v_max_f32_e32 v119, 0, v119
	v_max_f32_e32 v114, 0, v114
	v_max_f32_e32 v115, 0, v115
	v_max_f32_e32 v110, 0, v110
	v_max_f32_e32 v111, 0, v111
	v_max_f32_e32 v102, 0, v102
	v_max_f32_e32 v103, 0, v103
	v_lshl_add_u64 v[128:129], v[128:129], 0, v[130:131]
	v_pk_mul_f32 v[126:127], v[126:127], v[126:127]
	v_pk_mul_f32 v[122:123], v[122:123], v[122:123]
	v_pk_mul_f32 v[118:119], v[118:119], v[118:119]
	v_pk_mul_f32 v[114:115], v[114:115], v[114:115]
	v_pk_mul_f32 v[110:111], v[110:111], v[110:111]
	v_pk_mul_f32 v[102:103], v[102:103], v[102:103]
	global_store_dwordx2 v[128:129], v[168:169], off
	v_cvt_pk_bf16_f32 v169, v126, v127
	v_cvt_pk_bf16_f32 v127, v122, v123
	v_cvt_pk_bf16_f32 v123, v118, v119
	v_cvt_pk_bf16_f32 v119, v114, v115
	v_cvt_pk_bf16_f32 v115, v110, v111
	v_cvt_pk_bf16_f32 v111, v102, v103
	v_xor_b32_e32 v103, 0x80000000, v135
	v_xor_b32_e32 v102, 0x80000000, v134
	v_pk_fma_f32 v[124:125], v[152:153], v[132:133], v[124:125] op_sel_hi:[0,1,1] neg_lo:[1,0,0] neg_hi:[1,0,0]
	v_pk_fma_f32 v[120:121], v[156:157], v[132:133], v[120:121] op_sel_hi:[0,1,1] neg_lo:[1,0,0] neg_hi:[1,0,0]
	v_pk_fma_f32 v[116:117], v[184:185], v[132:133], v[116:117] op_sel_hi:[0,1,1] neg_lo:[1,0,0] neg_hi:[1,0,0]
	v_pk_fma_f32 v[112:113], v[180:181], v[132:133], v[112:113] op_sel_hi:[0,1,1] neg_lo:[1,0,0] neg_hi:[1,0,0]
	v_pk_fma_f32 v[108:109], v[164:165], v[132:133], v[108:109] op_sel_hi:[0,1,1] neg_lo:[1,0,0] neg_hi:[1,0,0]
	v_pk_fma_f32 v[100:101], v[162:163], v[132:133], v[100:101] op_sel_hi:[0,1,1] neg_lo:[1,0,0] neg_hi:[1,0,0]
	v_pk_fma_f32 v[92:93], v[132:133], v[160:161], v[92:93] op_sel_hi:[1,0,1] neg_lo:[1,0,0] neg_hi:[1,0,0]
	v_pk_fma_f32 v[94:95], v[102:103], v[160:161], v[94:95] op_sel_hi:[1,0,1]
	v_pk_fma_f32 v[124:125], v[154:155], v[124:125], v[136:137] op_sel_hi:[0,1,1]
	v_pk_fma_f32 v[120:121], v[158:159], v[120:121], v[136:137] op_sel_hi:[0,1,1]
	v_pk_fma_f32 v[116:117], v[190:191], v[116:117], v[136:137] op_sel_hi:[0,1,1]
	v_pk_fma_f32 v[112:113], v[188:189], v[112:113], v[136:137] op_sel_hi:[0,1,1]
	v_pk_fma_f32 v[108:109], v[186:187], v[108:109], v[136:137] op_sel_hi:[0,1,1]
	v_pk_fma_f32 v[100:101], v[182:183], v[100:101], v[136:137] op_sel_hi:[0,1,1]
	v_pk_fma_f32 v[94:95], v[94:95], v[166:167], v[138:139] op_sel_hi:[1,0,1]
	v_pk_fma_f32 v[92:93], v[92:93], v[166:167], v[136:137] op_sel_hi:[1,0,1]
	v_max_f32_e32 v124, 0, v124
	v_max_f32_e32 v125, 0, v125
	v_max_f32_e32 v120, 0, v120
	v_max_f32_e32 v121, 0, v121
	v_max_f32_e32 v116, 0, v116
	v_max_f32_e32 v117, 0, v117
	v_max_f32_e32 v112, 0, v112
	v_max_f32_e32 v113, 0, v113
	v_max_f32_e32 v108, 0, v108
	v_max_f32_e32 v109, 0, v109
	v_max_f32_e32 v100, 0, v100
	v_max_f32_e32 v101, 0, v101
	v_max_f32_e32 v92, 0, v92
	v_max_f32_e32 v93, 0, v93
	v_max_f32_e32 v94, 0, v94
	v_max_f32_e32 v95, 0, v95
	v_pk_mul_f32 v[124:125], v[124:125], v[124:125]
	v_pk_mul_f32 v[120:121], v[120:121], v[120:121]
	v_pk_mul_f32 v[116:117], v[116:117], v[116:117]
	v_pk_mul_f32 v[112:113], v[112:113], v[112:113]
	v_pk_mul_f32 v[108:109], v[108:109], v[108:109]
	v_pk_mul_f32 v[100:101], v[100:101], v[100:101]
	v_pk_mul_f32 v[94:95], v[94:95], v[94:95]
	v_pk_mul_f32 v[92:93], v[92:93], v[92:93]
	v_cvt_pk_bf16_f32 v168, v124, v125
	v_lshlrev_b64 v[124:125], 13, v[194:195]
	v_cvt_pk_bf16_f32 v126, v120, v121
	v_lshlrev_b64 v[120:121], 13, v[196:197]
	v_cvt_pk_bf16_f32 v122, v116, v117
	v_lshlrev_b64 v[116:117], 13, v[204:205]
	v_cvt_pk_bf16_f32 v118, v112, v113
	v_lshlrev_b64 v[112:113], 13, v[206:207]
	v_cvt_pk_bf16_f32 v114, v108, v109
; __device__ __forceinline__ u32x2 pk4(f32x4 v) { u32x2 r; r.x = pk2(v.x, v.y); r.y = pk2(v.z, v.w); return r; }
;     __device__ __forceinline__ void operator()(int row, int col, f32x4 v, int, float&, float&) const { *(u32x2*)(O + (size_t)row * ldc + col) = pk4(v * s); }
;     __device__ __forceinline__ void operator()(const f32x4 (&acc)[2][2][4][2], const pg8::Unit& u, int wr, int wc, int fr, int fq) const {
;     ...
; #pragma unroll
;                 for (int ai = 0; ai < 2; ++ai)
; #pragma unroll
;                     for (int m = 0; m < 4; ++m) {
;                         f32x4 v = acc[ai][bj][m][n];
;                         if (fold) v = (v - c1v * mu[ai][m]) * rs[ai][m] + c2v;
;                         f(u.pm * 256 + ai * 128 + wr * 64 + m * 16 + fr, col, v, fq, ps1[ai][m], ps2[ai][m]);
;                     }
;     __device__ __forceinline__ void operator()(int row, int col, f32x4 v, int, float&, float&) const {
;         f32x4 r; r.x = fmaxf(v.x, 0.f); r.y = fmaxf(v.y, 0.f); r.z = fmaxf(v.z, 0.f); r.w = fmaxf(v.w, 0.f);
;         *(u32x2*)(O + (size_t)row * FF + col) = pk4(r * r);
;     }
	v_lshlrev_b64 v[108:109], 13, v[202:203]
	v_cvt_pk_bf16_f32 v110, v100, v101
	v_lshlrev_b64 v[100:101], 13, v[200:201]
	v_cvt_pk_bf16_f32 v102, v92, v93
	v_cvt_pk_bf16_f32 v103, v94, v95
	v_lshlrev_b64 v[92:93], 13, v[198:199]
	v_add_u32_e32 v94, 16, v208
	v_lshl_add_u64 v[124:125], s[0:1], 0, v[124:125]
	v_lshl_add_u64 v[120:121], s[0:1], 0, v[120:121]
	v_lshl_add_u64 v[116:117], s[0:1], 0, v[116:117]
	v_lshl_add_u64 v[112:113], s[0:1], 0, v[112:113]
	v_lshl_add_u64 v[108:109], s[0:1], 0, v[108:109]
	v_lshl_add_u64 v[100:101], s[0:1], 0, v[100:101]
	v_lshl_add_u64 v[92:93], s[0:1], 0, v[92:93]
	v_ashrrev_i32_e32 v95, 31, v94
	v_lshl_add_u64 v[124:125], v[124:125], 0, v[130:131]
	v_lshl_add_u64 v[120:121], v[120:121], 0, v[130:131]
	v_lshl_add_u64 v[116:117], v[116:117], 0, v[130:131]
	v_lshl_add_u64 v[112:113], v[112:113], 0, v[130:131]
	v_lshl_add_u64 v[108:109], v[108:109], 0, v[130:131]
	v_lshl_add_u64 v[100:101], v[100:101], 0, v[130:131]
	v_lshl_add_u64 v[92:93], v[92:93], 0, v[130:131]
	v_lshlrev_b64 v[94:95], 2, v[94:95]
	v_and_b32_e32 v130, 3, v219
	v_lshrrev_b32_e32 v131, 2, v219
	v_lshl_add_u32 v130, v130, 4, v131
	v_lshlrev_b32_e32 v130, 2, v130
	v_and_b32_e32 v132, 15, v219
	v_sub_u32_e32 v132, v131, v132
	v_lshlrev_b32_e32 v132, 13, v132
	v_and_b32_e32 v131, 3, v219
	v_lshrrev_b32_e32 v133, 4, v219
	v_sub_u32_e32 v131, v131, v133
	v_lshl_add_u32 v132, v131, 3, v132
	v_ashrrev_i32_e32 v133, 31, v132
	ds_bpermute_b32 v136, v130, v168
	ds_bpermute_b32 v137, v130, v169
	v_lshl_add_u64 v[134:135], v[132:133], 0, v[124:125]
	ds_bpermute_b32 v200, v130, v126
	ds_bpermute_b32 v201, v130, v127
	v_lshl_add_u64 v[198:199], v[132:133], 0, v[120:121]
	ds_bpermute_b32 v204, v130, v122
	ds_bpermute_b32 v205, v130, v123
	v_lshl_add_u64 v[202:203], v[132:133], 0, v[116:117]
	s_waitcnt lgkmcnt(0)
	global_store_dwordx2 v[134:135], v[136:137], off
	global_store_dwordx2 v[198:199], v[200:201], off
	global_store_dwordx2 v[202:203], v[204:205], off
	ds_bpermute_b32 v136, v130, v118
	ds_bpermute_b32 v137, v130, v119
	v_lshl_add_u64 v[134:135], v[132:133], 0, v[112:113]
	ds_bpermute_b32 v200, v130, v114
	ds_bpermute_b32 v201, v130, v115
	v_lshl_add_u64 v[198:199], v[132:133], 0, v[108:109]
	ds_bpermute_b32 v204, v130, v110
	ds_bpermute_b32 v205, v130, v111
	v_lshl_add_u64 v[202:203], v[132:133], 0, v[100:101]
	s_waitcnt lgkmcnt(0)
	global_store_dwordx2 v[134:135], v[136:137], off
	global_store_dwordx2 v[198:199], v[200:201], off
	global_store_dwordx2 v[202:203], v[204:205], off
	ds_bpermute_b32 v136, v130, v102
	ds_bpermute_b32 v137, v130, v103
	v_lshl_add_u64 v[134:135], v[132:133], 0, v[92:93]
	s_waitcnt lgkmcnt(0)
	global_store_dwordx2 v[134:135], v[136:137], off
	v_lshl_add_u64 v[102:103], s[42:43], 0, v[94:95]
	ds_read_b128 v[130:133], v255 offset:64
	v_lshl_add_u64 v[94:95], s[46:47], 0, v[94:95]
	ds_read_b128 v[134:137], v255 offset:320
	s_mov_b64 s[0:1], -1
	s_waitcnt lgkmcnt(0)
	v_pk_fma_f32 v[94:95], v[148:149], v[130:131], v[104:105] op_sel_hi:[0,1,1] neg_lo:[1,0,0] neg_hi:[1,0,0]
	v_pk_fma_f32 v[102:103], v[148:149], v[132:133], v[106:107] op_sel_hi:[0,1,1] neg_lo:[1,0,0] neg_hi:[1,0,0]
	s_waitcnt lgkmcnt(0)
	v_pk_fma_f32 v[102:103], v[150:151], v[102:103], v[136:137] op_sel_hi:[0,1,1]
	v_pk_fma_f32 v[94:95], v[150:151], v[94:95], v[134:135] op_sel_hi:[0,1,1]
	v_max_f32_e32 v94, 0, v94
	v_max_f32_e32 v95, 0, v95
	v_max_f32_e32 v102, 0, v102
	v_max_f32_e32 v103, 0, v103
	v_pk_fma_f32 v[64:65], v[160:161], v[130:131], v[64:65] op_sel_hi:[0,1,1] neg_lo:[1,0,0] neg_hi:[1,0,0]
	v_pk_fma_f32 v[66:67], v[160:161], v[132:133], v[66:67] op_sel_hi:[0,1,1] neg_lo:[1,0,0] neg_hi:[1,0,0]
	v_pk_mul_f32 v[102:103], v[102:103], v[102:103]
	v_pk_mul_f32 v[94:95], v[94:95], v[94:95]
	v_pk_fma_f32 v[66:67], v[166:167], v[66:67], v[136:137] op_sel_hi:[0,1,1]
	v_pk_fma_f32 v[64:65], v[166:167], v[64:65], v[134:135] op_sel_hi:[0,1,1]
	v_cvt_pk_bf16_f32 v94, v94, v95
	v_cvt_pk_bf16_f32 v95, v102, v103
	v_pk_fma_f32 v[72:73], v[162:163], v[130:131], v[72:73] op_sel_hi:[0,1,1] neg_lo:[1,0,0] neg_hi:[1,0,0]
	v_pk_fma_f32 v[74:75], v[162:163], v[132:133], v[74:75] op_sel_hi:[0,1,1] neg_lo:[1,0,0] neg_hi:[1,0,0]
	v_max_f32_e32 v64, 0, v64
	v_max_f32_e32 v65, 0, v65
	v_max_f32_e32 v66, 0, v66
	v_max_f32_e32 v67, 0, v67
	v_and_b32_e32 v198, 3, v219
	v_lshrrev_b32_e32 v199, 2, v219
	v_lshl_add_u32 v198, v198, 4, v199
	v_lshlrev_b32_e32 v198, 2, v198
	v_and_b32_e32 v200, 15, v219
	v_sub_u32_e32 v200, v199, v200
	v_lshlrev_b32_e32 v200, 13, v200
	v_and_b32_e32 v199, 3, v219
	v_lshrrev_b32_e32 v201, 4, v219
	v_sub_u32_e32 v199, v199, v201
	v_lshl_add_u32 v200, v199, 3, v200
	v_ashrrev_i32_e32 v201, 31, v200
	ds_bpermute_b32 v204, v198, v94
	ds_bpermute_b32 v205, v198, v95
	v_lshl_add_u64 v[202:203], v[200:201], 0, v[128:129]
	s_waitcnt lgkmcnt(0)
; __device__ __forceinline__ u32x2 pk4(f32x4 v) { u32x2 r; r.x = pk2(v.x, v.y); r.y = pk2(v.z, v.w); return r; }
;     __device__ __forceinline__ void operator()(int row, int col, f32x4 v, int, float&, float&) const { *(u32x2*)(O + (size_t)row * ldc + col) = pk4(v * s); }
;     __device__ __forceinline__ void operator()(const f32x4 (&acc)[2][2][4][2], const pg8::Unit& u, int wr, int wc, int fr, int fq) const {
;     ...
;         for (int bj = 0; bj < 2; ++bj)
; #pragma unroll
;             for (int n = 0; n < 2; ++n) {
;                 const int col = u.pn * 256 + bj * 128 + wc * 32 + n * 16 + fq * 4;
;                 f32x4 c1v = (f32x4){0.f, 0.f, 0.f, 0.f}, c2v = c1v;
;                 if (fold) { c1v = *(const f32x4*)(c1 + col); c2v = *(const f32x4*)(c2 + col); }
; #pragma unroll
;                 for (int ai = 0; ai < 2; ++ai)
; #pragma unroll
;                     for (int m = 0; m < 4; ++m) {
;                         f32x4 v = acc[ai][bj][m][n];
;                         if (fold) v = (v - c1v * mu[ai][m]) * rs[ai][m] + c2v;
;                         f(u.pm * 256 + ai * 128 + wr * 64 + m * 16 + fr, col, v, fq, ps1[ai][m], ps2[ai][m]);
;                     }
;     __device__ __forceinline__ void operator()(int row, int col, f32x4 v, int, float&, float&) const {
;         f32x4 r; r.x = fmaxf(v.x, 0.f); r.y = fmaxf(v.y, 0.f); r.z = fmaxf(v.z, 0.f); r.w = fmaxf(v.w, 0.f);
;         *(u32x2*)(O + (size_t)row * FF + col) = pk4(r * r);
;     }
	global_store_dwordx2 v[202:203], v[204:205], off offset:32
	v_pk_fma_f32 v[94:95], v[152:153], v[130:131], v[96:97] op_sel_hi:[0,1,1] neg_lo:[1,0,0] neg_hi:[1,0,0]
	v_pk_fma_f32 v[96:97], v[152:153], v[132:133], v[98:99] op_sel_hi:[0,1,1] neg_lo:[1,0,0] neg_hi:[1,0,0]
	v_pk_fma_f32 v[88:89], v[156:157], v[130:131], v[88:89] op_sel_hi:[0,1,1] neg_lo:[1,0,0] neg_hi:[1,0,0]
	v_pk_fma_f32 v[90:91], v[156:157], v[132:133], v[90:91] op_sel_hi:[0,1,1] neg_lo:[1,0,0] neg_hi:[1,0,0]
	v_pk_fma_f32 v[84:85], v[184:185], v[130:131], v[84:85] op_sel_hi:[0,1,1] neg_lo:[1,0,0] neg_hi:[1,0,0]
	v_pk_fma_f32 v[86:87], v[184:185], v[132:133], v[86:87] op_sel_hi:[0,1,1] neg_lo:[1,0,0] neg_hi:[1,0,0]
	v_pk_fma_f32 v[80:81], v[180:181], v[130:131], v[80:81] op_sel_hi:[0,1,1] neg_lo:[1,0,0] neg_hi:[1,0,0]
	v_pk_fma_f32 v[82:83], v[180:181], v[132:133], v[82:83] op_sel_hi:[0,1,1] neg_lo:[1,0,0] neg_hi:[1,0,0]
	v_pk_fma_f32 v[76:77], v[164:165], v[130:131], v[76:77] op_sel_hi:[0,1,1] neg_lo:[1,0,0] neg_hi:[1,0,0]
	v_pk_fma_f32 v[78:79], v[164:165], v[132:133], v[78:79] op_sel_hi:[0,1,1] neg_lo:[1,0,0] neg_hi:[1,0,0]
	v_pk_fma_f32 v[74:75], v[182:183], v[74:75], v[136:137] op_sel_hi:[0,1,1]
	v_pk_fma_f32 v[72:73], v[182:183], v[72:73], v[134:135] op_sel_hi:[0,1,1]
	v_pk_mul_f32 v[66:67], v[66:67], v[66:67]
	v_pk_mul_f32 v[64:65], v[64:65], v[64:65]
	v_pk_fma_f32 v[96:97], v[154:155], v[96:97], v[136:137] op_sel_hi:[0,1,1]
	v_pk_fma_f32 v[94:95], v[154:155], v[94:95], v[134:135] op_sel_hi:[0,1,1]
	v_pk_fma_f32 v[90:91], v[158:159], v[90:91], v[136:137] op_sel_hi:[0,1,1]
	v_pk_fma_f32 v[88:89], v[158:159], v[88:89], v[134:135] op_sel_hi:[0,1,1]
	v_pk_fma_f32 v[86:87], v[190:191], v[86:87], v[136:137] op_sel_hi:[0,1,1]
	v_pk_fma_f32 v[84:85], v[190:191], v[84:85], v[134:135] op_sel_hi:[0,1,1]
	v_pk_fma_f32 v[82:83], v[188:189], v[82:83], v[136:137] op_sel_hi:[0,1,1]
	v_pk_fma_f32 v[80:81], v[188:189], v[80:81], v[134:135] op_sel_hi:[0,1,1]
	v_pk_fma_f32 v[78:79], v[186:187], v[78:79], v[136:137] op_sel_hi:[0,1,1]
	v_pk_fma_f32 v[76:77], v[186:187], v[76:77], v[134:135] op_sel_hi:[0,1,1]
	v_max_f32_e32 v72, 0, v72
	v_max_f32_e32 v73, 0, v73
	v_max_f32_e32 v74, 0, v74
	v_max_f32_e32 v75, 0, v75
	v_cvt_pk_bf16_f32 v64, v64, v65
	v_cvt_pk_bf16_f32 v65, v66, v67
	v_max_f32_e32 v94, 0, v94
	v_max_f32_e32 v95, 0, v95
	v_max_f32_e32 v96, 0, v96
	v_max_f32_e32 v97, 0, v97
	v_max_f32_e32 v88, 0, v88
	v_max_f32_e32 v89, 0, v89
	v_max_f32_e32 v90, 0, v90
	v_max_f32_e32 v91, 0, v91
	v_max_f32_e32 v84, 0, v84
	v_max_f32_e32 v85, 0, v85
	v_max_f32_e32 v86, 0, v86
	v_max_f32_e32 v87, 0, v87
	v_max_f32_e32 v80, 0, v80
	v_max_f32_e32 v81, 0, v81
	v_max_f32_e32 v82, 0, v82
	v_max_f32_e32 v83, 0, v83
	v_max_f32_e32 v76, 0, v76
	v_max_f32_e32 v77, 0, v77
	v_max_f32_e32 v78, 0, v78
	v_max_f32_e32 v79, 0, v79
	v_pk_mul_f32 v[74:75], v[74:75], v[74:75]
	v_pk_mul_f32 v[72:73], v[72:73], v[72:73]
	v_and_b32_e32 v66, 3, v219
	v_lshrrev_b32_e32 v67, 2, v219
	v_lshl_add_u32 v66, v66, 4, v67
	v_lshlrev_b32_e32 v66, 2, v66
	v_and_b32_e32 v198, 15, v219
	v_sub_u32_e32 v198, v67, v198
	v_lshlrev_b32_e32 v198, 13, v198
	v_and_b32_e32 v67, 3, v219
	v_lshrrev_b32_e32 v199, 4, v219
	v_sub_u32_e32 v67, v67, v199
	v_lshl_add_u32 v198, v67, 3, v198
	v_ashrrev_i32_e32 v199, 31, v198
	ds_bpermute_b32 v202, v66, v64
	ds_bpermute_b32 v203, v66, v65
	v_lshl_add_u64 v[200:201], v[198:199], 0, v[92:93]
	s_waitcnt lgkmcnt(0)
	global_store_dwordx2 v[200:201], v[202:203], off offset:32
	v_add_u32_e32 v64, 0x80, v208
	v_pk_mul_f32 v[96:97], v[96:97], v[96:97]
	v_pk_mul_f32 v[94:95], v[94:95], v[94:95]
	v_pk_mul_f32 v[90:91], v[90:91], v[90:91]
	v_pk_mul_f32 v[88:89], v[88:89], v[88:89]
	v_pk_mul_f32 v[86:87], v[86:87], v[86:87]
	v_pk_mul_f32 v[84:85], v[84:85], v[84:85]
	v_pk_mul_f32 v[82:83], v[82:83], v[82:83]
	v_pk_mul_f32 v[80:81], v[80:81], v[80:81]
	v_pk_mul_f32 v[78:79], v[78:79], v[78:79]
	v_pk_mul_f32 v[76:77], v[76:77], v[76:77]
	v_cvt_pk_bf16_f32 v72, v72, v73
	v_cvt_pk_bf16_f32 v73, v74, v75
	v_ashrrev_i32_e32 v65, 31, v64
	v_cvt_pk_bf16_f32 v94, v94, v95
	v_cvt_pk_bf16_f32 v95, v96, v97
	v_cvt_pk_bf16_f32 v88, v88, v89
	v_cvt_pk_bf16_f32 v89, v90, v91
	v_cvt_pk_bf16_f32 v84, v84, v85
	v_cvt_pk_bf16_f32 v85, v86, v87
	v_cvt_pk_bf16_f32 v80, v80, v81
	v_cvt_pk_bf16_f32 v81, v82, v83
	v_cvt_pk_bf16_f32 v76, v76, v77
	v_cvt_pk_bf16_f32 v77, v78, v79
	v_and_b32_e32 v66, 3, v219
	v_lshrrev_b32_e32 v67, 2, v219
	v_lshl_add_u32 v66, v66, 4, v67
	v_lshlrev_b32_e32 v66, 2, v66
	v_and_b32_e32 v74, 15, v219
	v_sub_u32_e32 v74, v67, v74
	v_lshlrev_b32_e32 v74, 13, v74
	v_and_b32_e32 v67, 3, v219
	v_lshrrev_b32_e32 v75, 4, v219
	v_sub_u32_e32 v67, v67, v75
	v_lshl_add_u32 v74, v67, 3, v74
	v_ashrrev_i32_e32 v75, 31, v74
	ds_bpermute_b32 v200, v66, v72
	ds_bpermute_b32 v201, v66, v73
	v_lshl_add_u64 v[198:199], v[74:75], 0, v[100:101]
	s_waitcnt lgkmcnt(0)
	global_store_dwordx2 v[198:199], v[200:201], off offset:32
	v_lshlrev_b64 v[72:73], 2, v[64:65]
	v_and_b32_e32 v64, 3, v219
	v_lshrrev_b32_e32 v65, 2, v219
	v_lshl_add_u32 v64, v64, 4, v65
	v_lshlrev_b32_e32 v64, 2, v64
	v_and_b32_e32 v66, 15, v219
	v_sub_u32_e32 v66, v65, v66
	v_lshlrev_b32_e32 v66, 13, v66
	v_and_b32_e32 v65, 3, v219
	v_lshrrev_b32_e32 v67, 4, v219
	v_sub_u32_e32 v65, v65, v67
	v_lshl_add_u32 v66, v65, 3, v66
	v_ashrrev_i32_e32 v67, 31, v66
	ds_bpermute_b32 v198, v64, v94
	ds_bpermute_b32 v199, v64, v95
	v_lshl_add_u64 v[74:75], v[66:67], 0, v[124:125]
	ds_bpermute_b32 v202, v64, v88
	ds_bpermute_b32 v203, v64, v89
	v_lshl_add_u64 v[200:201], v[66:67], 0, v[120:121]
	s_waitcnt lgkmcnt(0)
; __device__ __forceinline__ u32x2 pk4(f32x4 v) { u32x2 r; r.x = pk2(v.x, v.y); r.y = pk2(v.z, v.w); return r; }
;     __device__ __forceinline__ void operator()(int row, int col, f32x4 v, int, float&, float&) const { *(u32x2*)(O + (size_t)row * ldc + col) = pk4(v * s); }
;     __device__ __forceinline__ void operator()(const f32x4 (&acc)[2][2][4][2], const pg8::Unit& u, int wr, int wc, int fr, int fq) const {
;     ...
;         for (int bj = 0; bj < 2; ++bj)
; #pragma unroll
;             for (int n = 0; n < 2; ++n) {
;                 const int col = u.pn * 256 + bj * 128 + wc * 32 + n * 16 + fq * 4;
;                 f32x4 c1v = (f32x4){0.f, 0.f, 0.f, 0.f}, c2v = c1v;
;                 if (fold) { c1v = *(const f32x4*)(c1 + col); c2v = *(const f32x4*)(c2 + col); }
; #pragma unroll
;                 for (int ai = 0; ai < 2; ++ai)
; #pragma unroll
;                     for (int m = 0; m < 4; ++m) {
;                         f32x4 v = acc[ai][bj][m][n];
;                         if (fold) v = (v - c1v * mu[ai][m]) * rs[ai][m] + c2v;
;                         f(u.pm * 256 + ai * 128 + wr * 64 + m * 16 + fr, col, v, fq, ps1[ai][m], ps2[ai][m]);
;                     }
;     __device__ __forceinline__ void operator()(int row, int col, f32x4 v, int, float&, float&) const {
;         f32x4 r; r.x = fmaxf(v.x, 0.f); r.y = fmaxf(v.y, 0.f); r.z = fmaxf(v.z, 0.f); r.w = fmaxf(v.w, 0.f);
;         *(u32x2*)(O + (size_t)row * FF + col) = pk4(r * r);
;     }
	global_store_dwordx2 v[74:75], v[198:199], off offset:32
	global_store_dwordx2 v[200:201], v[202:203], off offset:32
	ds_bpermute_b32 v198, v64, v84
	ds_bpermute_b32 v199, v64, v85
	v_lshl_add_u64 v[74:75], v[66:67], 0, v[116:117]
	ds_bpermute_b32 v202, v64, v80
	ds_bpermute_b32 v203, v64, v81
	v_lshl_add_u64 v[200:201], v[66:67], 0, v[112:113]
	s_waitcnt lgkmcnt(0)
	global_store_dwordx2 v[74:75], v[198:199], off offset:32
	global_store_dwordx2 v[200:201], v[202:203], off offset:32
	ds_bpermute_b32 v198, v64, v76
	ds_bpermute_b32 v199, v64, v77
	v_lshl_add_u64 v[74:75], v[66:67], 0, v[108:109]
	s_waitcnt lgkmcnt(0)
	global_store_dwordx2 v[74:75], v[198:199], off offset:32
	v_lshl_add_u64 v[64:65], s[42:43], 0, v[72:73]
	ds_read_b128 v[64:67], v255 offset:128
	v_lshl_add_u64 v[72:73], s[46:47], 0, v[72:73]
	ds_read_b128 v[72:75], v255 offset:384
	s_waitcnt lgkmcnt(0)
	v_pk_fma_f32 v[28:29], v[160:161], v[64:65], v[28:29] op_sel_hi:[0,1,1] neg_lo:[1,0,0] neg_hi:[1,0,0]
	v_pk_fma_f32 v[30:31], v[160:161], v[66:67], v[30:31] op_sel_hi:[0,1,1] neg_lo:[1,0,0] neg_hi:[1,0,0]
	s_waitcnt lgkmcnt(0)
	v_pk_fma_f32 v[30:31], v[166:167], v[30:31], v[74:75] op_sel_hi:[0,1,1]
	v_pk_fma_f32 v[28:29], v[166:167], v[28:29], v[72:73] op_sel_hi:[0,1,1]
	v_pk_fma_f32 v[36:37], v[162:163], v[64:65], v[36:37] op_sel_hi:[0,1,1] neg_lo:[1,0,0] neg_hi:[1,0,0]
	v_pk_fma_f32 v[38:39], v[162:163], v[66:67], v[38:39] op_sel_hi:[0,1,1] neg_lo:[1,0,0] neg_hi:[1,0,0]
	v_max_f32_e32 v28, 0, v28
	v_max_f32_e32 v29, 0, v29
	v_max_f32_e32 v30, 0, v30
	v_max_f32_e32 v31, 0, v31
	v_pk_fma_f32 v[68:69], v[148:149], v[64:65], v[68:69] op_sel_hi:[0,1,1] neg_lo:[1,0,0] neg_hi:[1,0,0]
	v_pk_fma_f32 v[70:71], v[148:149], v[66:67], v[70:71] op_sel_hi:[0,1,1] neg_lo:[1,0,0] neg_hi:[1,0,0]
	v_pk_fma_f32 v[60:61], v[152:153], v[64:65], v[60:61] op_sel_hi:[0,1,1] neg_lo:[1,0,0] neg_hi:[1,0,0]
	v_pk_fma_f32 v[62:63], v[152:153], v[66:67], v[62:63] op_sel_hi:[0,1,1] neg_lo:[1,0,0] neg_hi:[1,0,0]
	v_pk_fma_f32 v[56:57], v[156:157], v[64:65], v[56:57] op_sel_hi:[0,1,1] neg_lo:[1,0,0] neg_hi:[1,0,0]
	v_pk_fma_f32 v[58:59], v[156:157], v[66:67], v[58:59] op_sel_hi:[0,1,1] neg_lo:[1,0,0] neg_hi:[1,0,0]
	v_pk_fma_f32 v[52:53], v[184:185], v[64:65], v[52:53] op_sel_hi:[0,1,1] neg_lo:[1,0,0] neg_hi:[1,0,0]
	v_pk_fma_f32 v[54:55], v[184:185], v[66:67], v[54:55] op_sel_hi:[0,1,1] neg_lo:[1,0,0] neg_hi:[1,0,0]
	v_pk_fma_f32 v[48:49], v[180:181], v[64:65], v[48:49] op_sel_hi:[0,1,1] neg_lo:[1,0,0] neg_hi:[1,0,0]
	v_pk_fma_f32 v[50:51], v[180:181], v[66:67], v[50:51] op_sel_hi:[0,1,1] neg_lo:[1,0,0] neg_hi:[1,0,0]
	v_pk_fma_f32 v[44:45], v[164:165], v[64:65], v[44:45] op_sel_hi:[0,1,1] neg_lo:[1,0,0] neg_hi:[1,0,0]
	v_pk_fma_f32 v[46:47], v[164:165], v[66:67], v[46:47] op_sel_hi:[0,1,1] neg_lo:[1,0,0] neg_hi:[1,0,0]
	v_pk_fma_f32 v[38:39], v[182:183], v[38:39], v[74:75] op_sel_hi:[0,1,1]
	v_pk_fma_f32 v[36:37], v[182:183], v[36:37], v[72:73] op_sel_hi:[0,1,1]
	v_pk_mul_f32 v[30:31], v[30:31], v[30:31]
	v_pk_mul_f32 v[28:29], v[28:29], v[28:29]
	v_pk_fma_f32 v[70:71], v[150:151], v[70:71], v[74:75] op_sel_hi:[0,1,1]
	v_pk_fma_f32 v[68:69], v[150:151], v[68:69], v[72:73] op_sel_hi:[0,1,1]
	v_pk_fma_f32 v[62:63], v[154:155], v[62:63], v[74:75] op_sel_hi:[0,1,1]
	v_pk_fma_f32 v[60:61], v[154:155], v[60:61], v[72:73] op_sel_hi:[0,1,1]
	v_pk_fma_f32 v[58:59], v[158:159], v[58:59], v[74:75] op_sel_hi:[0,1,1]
	v_pk_fma_f32 v[56:57], v[158:159], v[56:57], v[72:73] op_sel_hi:[0,1,1]
	v_pk_fma_f32 v[54:55], v[190:191], v[54:55], v[74:75] op_sel_hi:[0,1,1]
	v_pk_fma_f32 v[52:53], v[190:191], v[52:53], v[72:73] op_sel_hi:[0,1,1]
	v_pk_fma_f32 v[50:51], v[188:189], v[50:51], v[74:75] op_sel_hi:[0,1,1]
	v_pk_fma_f32 v[48:49], v[188:189], v[48:49], v[72:73] op_sel_hi:[0,1,1]
	v_pk_fma_f32 v[46:47], v[186:187], v[46:47], v[74:75] op_sel_hi:[0,1,1]
	v_pk_fma_f32 v[44:45], v[186:187], v[44:45], v[72:73] op_sel_hi:[0,1,1]
	v_max_f32_e32 v36, 0, v36
	v_max_f32_e32 v37, 0, v37
	v_max_f32_e32 v38, 0, v38
	v_max_f32_e32 v39, 0, v39
	v_cvt_pk_bf16_f32 v28, v28, v29
	v_cvt_pk_bf16_f32 v29, v30, v31
	v_max_f32_e32 v68, 0, v68
	v_max_f32_e32 v69, 0, v69
	v_max_f32_e32 v70, 0, v70
	v_max_f32_e32 v71, 0, v71
	v_max_f32_e32 v60, 0, v60
	v_max_f32_e32 v61, 0, v61
	v_max_f32_e32 v62, 0, v62
	v_max_f32_e32 v63, 0, v63
	v_max_f32_e32 v56, 0, v56
	v_max_f32_e32 v57, 0, v57
	v_max_f32_e32 v58, 0, v58
	v_max_f32_e32 v59, 0, v59
	v_max_f32_e32 v52, 0, v52
	v_max_f32_e32 v53, 0, v53
	v_max_f32_e32 v54, 0, v54
	v_max_f32_e32 v55, 0, v55
	v_max_f32_e32 v48, 0, v48
	v_max_f32_e32 v49, 0, v49
	v_max_f32_e32 v50, 0, v50
	v_max_f32_e32 v51, 0, v51
	v_max_f32_e32 v44, 0, v44
	v_max_f32_e32 v45, 0, v45
	v_max_f32_e32 v46, 0, v46
	v_max_f32_e32 v47, 0, v47
	v_pk_mul_f32 v[38:39], v[38:39], v[38:39]
	v_pk_mul_f32 v[36:37], v[36:37], v[36:37]
	v_and_b32_e32 v30, 3, v219
	v_lshrrev_b32_e32 v31, 2, v219
	v_lshl_add_u32 v30, v30, 4, v31
	v_lshlrev_b32_e32 v30, 2, v30
	v_and_b32_e32 v198, 15, v219
	v_sub_u32_e32 v198, v31, v198
	v_lshlrev_b32_e32 v198, 13, v198
	v_and_b32_e32 v31, 3, v219
	v_lshrrev_b32_e32 v199, 4, v219
	v_sub_u32_e32 v31, v31, v199
	v_lshl_add_u32 v198, v31, 3, v198
	v_ashrrev_i32_e32 v199, 31, v198
	ds_bpermute_b32 v202, v30, v28
	ds_bpermute_b32 v203, v30, v29
	v_lshl_add_u64 v[200:201], v[198:199], 0, v[92:93]
	s_waitcnt lgkmcnt(0)
; __device__ __forceinline__ u32x2 pk4(f32x4 v) { u32x2 r; r.x = pk2(v.x, v.y); r.y = pk2(v.z, v.w); return r; }
;     __device__ __forceinline__ void operator()(int row, int col, f32x4 v, int, float&, float&) const { *(u32x2*)(O + (size_t)row * ldc + col) = pk4(v * s); }
;     __device__ __forceinline__ void operator()(const f32x4 (&acc)[2][2][4][2], const pg8::Unit& u, int wr, int wc, int fr, int fq) const {
;     ...
;         for (int bj = 0; bj < 2; ++bj)
; #pragma unroll
;             for (int n = 0; n < 2; ++n) {
;                 const int col = u.pn * 256 + bj * 128 + wc * 32 + n * 16 + fq * 4;
;                 f32x4 c1v = (f32x4){0.f, 0.f, 0.f, 0.f}, c2v = c1v;
;                 if (fold) { c1v = *(const f32x4*)(c1 + col); c2v = *(const f32x4*)(c2 + col); }
; #pragma unroll
;                 for (int ai = 0; ai < 2; ++ai)
; #pragma unroll
;                     for (int m = 0; m < 4; ++m) {
;                         f32x4 v = acc[ai][bj][m][n];
;                         if (fold) v = (v - c1v * mu[ai][m]) * rs[ai][m] + c2v;
;                         f(u.pm * 256 + ai * 128 + wr * 64 + m * 16 + fr, col, v, fq, ps1[ai][m], ps2[ai][m]);
;                     }
;     __device__ __forceinline__ void operator()(int row, int col, f32x4 v, int, float&, float&) const {
;         f32x4 r; r.x = fmaxf(v.x, 0.f); r.y = fmaxf(v.y, 0.f); r.z = fmaxf(v.z, 0.f); r.w = fmaxf(v.w, 0.f);
;         *(u32x2*)(O + (size_t)row * FF + col) = pk4(r * r);
;     }
	global_store_dwordx2 v[200:201], v[202:203], off offset:256
	v_add_u32_e32 v28, 0x90, v208
	v_pk_mul_f32 v[70:71], v[70:71], v[70:71]
	v_pk_mul_f32 v[68:69], v[68:69], v[68:69]
	v_pk_mul_f32 v[62:63], v[62:63], v[62:63]
	v_pk_mul_f32 v[60:61], v[60:61], v[60:61]
	v_pk_mul_f32 v[58:59], v[58:59], v[58:59]
	v_pk_mul_f32 v[56:57], v[56:57], v[56:57]
	v_pk_mul_f32 v[54:55], v[54:55], v[54:55]
	v_pk_mul_f32 v[52:53], v[52:53], v[52:53]
	v_pk_mul_f32 v[50:51], v[50:51], v[50:51]
	v_pk_mul_f32 v[48:49], v[48:49], v[48:49]
	v_pk_mul_f32 v[46:47], v[46:47], v[46:47]
	v_pk_mul_f32 v[44:45], v[44:45], v[44:45]
	v_cvt_pk_bf16_f32 v36, v36, v37
	v_cvt_pk_bf16_f32 v37, v38, v39
	v_ashrrev_i32_e32 v29, 31, v28
	v_cvt_pk_bf16_f32 v68, v68, v69
	v_cvt_pk_bf16_f32 v69, v70, v71
	v_cvt_pk_bf16_f32 v60, v60, v61
	v_cvt_pk_bf16_f32 v61, v62, v63
	v_cvt_pk_bf16_f32 v56, v56, v57
	v_cvt_pk_bf16_f32 v57, v58, v59
	v_cvt_pk_bf16_f32 v52, v52, v53
	v_cvt_pk_bf16_f32 v53, v54, v55
	v_cvt_pk_bf16_f32 v48, v48, v49
	v_cvt_pk_bf16_f32 v49, v50, v51
	v_cvt_pk_bf16_f32 v44, v44, v45
	v_cvt_pk_bf16_f32 v45, v46, v47
	v_and_b32_e32 v30, 3, v219
	v_lshrrev_b32_e32 v31, 2, v219
	v_lshl_add_u32 v30, v30, 4, v31
	v_lshlrev_b32_e32 v30, 2, v30
	v_and_b32_e32 v38, 15, v219
	v_sub_u32_e32 v38, v31, v38
	v_lshlrev_b32_e32 v38, 13, v38
	v_and_b32_e32 v31, 3, v219
	v_lshrrev_b32_e32 v39, 4, v219
	v_sub_u32_e32 v31, v31, v39
	v_lshl_add_u32 v38, v31, 3, v38
	v_ashrrev_i32_e32 v39, 31, v38
	ds_bpermute_b32 v200, v30, v36
	ds_bpermute_b32 v201, v30, v37
	v_lshl_add_u64 v[198:199], v[38:39], 0, v[100:101]
	s_waitcnt lgkmcnt(0)
	global_store_dwordx2 v[198:199], v[200:201], off offset:256
	v_lshlrev_b64 v[36:37], 2, v[28:29]
	v_and_b32_e32 v28, 3, v219
	v_lshrrev_b32_e32 v29, 2, v219
	v_lshl_add_u32 v28, v28, 4, v29
	v_lshlrev_b32_e32 v28, 2, v28
	v_and_b32_e32 v30, 15, v219
	v_sub_u32_e32 v30, v29, v30
	v_lshlrev_b32_e32 v30, 13, v30
	v_and_b32_e32 v29, 3, v219
	v_lshrrev_b32_e32 v31, 4, v219
	v_sub_u32_e32 v29, v29, v31
	v_lshl_add_u32 v30, v29, 3, v30
	v_ashrrev_i32_e32 v31, 31, v30
	ds_bpermute_b32 v198, v28, v68
	ds_bpermute_b32 v199, v28, v69
	v_lshl_add_u64 v[38:39], v[30:31], 0, v[128:129]
	ds_bpermute_b32 v202, v28, v60
	ds_bpermute_b32 v203, v28, v61
	v_lshl_add_u64 v[200:201], v[30:31], 0, v[124:125]
	s_waitcnt lgkmcnt(0)
	global_store_dwordx2 v[38:39], v[198:199], off offset:256
	global_store_dwordx2 v[200:201], v[202:203], off offset:256
	ds_bpermute_b32 v198, v28, v56
	ds_bpermute_b32 v199, v28, v57
	v_lshl_add_u64 v[38:39], v[30:31], 0, v[120:121]
	ds_bpermute_b32 v202, v28, v52
	ds_bpermute_b32 v203, v28, v53
	v_lshl_add_u64 v[200:201], v[30:31], 0, v[116:117]
	s_waitcnt lgkmcnt(0)
	global_store_dwordx2 v[38:39], v[198:199], off offset:256
	global_store_dwordx2 v[200:201], v[202:203], off offset:256
	ds_bpermute_b32 v198, v28, v48
	ds_bpermute_b32 v199, v28, v49
	v_lshl_add_u64 v[38:39], v[30:31], 0, v[112:113]
	ds_bpermute_b32 v202, v28, v44
	ds_bpermute_b32 v203, v28, v45
	v_lshl_add_u64 v[200:201], v[30:31], 0, v[108:109]
	s_waitcnt lgkmcnt(0)
	global_store_dwordx2 v[38:39], v[198:199], off offset:256
	global_store_dwordx2 v[200:201], v[202:203], off offset:256
	v_lshl_add_u64 v[28:29], s[42:43], 0, v[36:37]
	ds_read_b128 v[28:31], v255 offset:192
	v_lshl_add_u64 v[36:37], s[46:47], 0, v[36:37]
	ds_read_b128 v[36:39], v255 offset:448
	s_waitcnt lgkmcnt(0)
	v_pk_fma_f32 v[40:41], v[148:149], v[28:29], v[40:41] op_sel_hi:[0,1,1] neg_lo:[1,0,0] neg_hi:[1,0,0]
	v_pk_fma_f32 v[42:43], v[148:149], v[30:31], v[42:43] op_sel_hi:[0,1,1] neg_lo:[1,0,0] neg_hi:[1,0,0]
	v_pk_fma_f32 v[32:33], v[152:153], v[28:29], v[32:33] op_sel_hi:[0,1,1] neg_lo:[1,0,0] neg_hi:[1,0,0]
	v_pk_fma_f32 v[34:35], v[152:153], v[30:31], v[34:35] op_sel_hi:[0,1,1] neg_lo:[1,0,0] neg_hi:[1,0,0]
	v_pk_fma_f32 v[24:25], v[156:157], v[28:29], v[24:25] op_sel_hi:[0,1,1] neg_lo:[1,0,0] neg_hi:[1,0,0]
	v_pk_fma_f32 v[26:27], v[156:157], v[30:31], v[26:27] op_sel_hi:[0,1,1] neg_lo:[1,0,0] neg_hi:[1,0,0]
	v_pk_fma_f32 v[20:21], v[184:185], v[28:29], v[20:21] op_sel_hi:[0,1,1] neg_lo:[1,0,0] neg_hi:[1,0,0]
	v_pk_fma_f32 v[22:23], v[184:185], v[30:31], v[22:23] op_sel_hi:[0,1,1] neg_lo:[1,0,0] neg_hi:[1,0,0]
	v_pk_fma_f32 v[16:17], v[180:181], v[28:29], v[16:17] op_sel_hi:[0,1,1] neg_lo:[1,0,0] neg_hi:[1,0,0]
	v_pk_fma_f32 v[18:19], v[180:181], v[30:31], v[18:19] op_sel_hi:[0,1,1] neg_lo:[1,0,0] neg_hi:[1,0,0]
	v_pk_fma_f32 v[12:13], v[164:165], v[28:29], v[12:13] op_sel_hi:[0,1,1] neg_lo:[1,0,0] neg_hi:[1,0,0]
	v_pk_fma_f32 v[14:15], v[164:165], v[30:31], v[14:15] op_sel_hi:[0,1,1] neg_lo:[1,0,0] neg_hi:[1,0,0]
	v_pk_fma_f32 v[8:9], v[162:163], v[28:29], v[8:9] op_sel_hi:[0,1,1] neg_lo:[1,0,0] neg_hi:[1,0,0]
	v_pk_fma_f32 v[10:11], v[162:163], v[30:31], v[10:11] op_sel_hi:[0,1,1] neg_lo:[1,0,0] neg_hi:[1,0,0]
	v_pk_fma_f32 v[4:5], v[160:161], v[28:29], v[4:5] op_sel_hi:[0,1,1] neg_lo:[1,0,0] neg_hi:[1,0,0]
	v_pk_fma_f32 v[6:7], v[160:161], v[30:31], v[6:7] op_sel_hi:[0,1,1] neg_lo:[1,0,0] neg_hi:[1,0,0]
	s_waitcnt lgkmcnt(0)
; __device__ __forceinline__ u32x2 pk4(f32x4 v) { u32x2 r; r.x = pk2(v.x, v.y); r.y = pk2(v.z, v.w); return r; }
;     __device__ __forceinline__ void operator()(int row, int col, f32x4 v, int, float&, float&) const { *(u32x2*)(O + (size_t)row * ldc + col) = pk4(v * s); }
;     __device__ __forceinline__ void operator()(const f32x4 (&acc)[2][2][4][2], const pg8::Unit& u, int wr, int wc, int fr, int fq) const {
;     ...
;         for (int bj = 0; bj < 2; ++bj)
; #pragma unroll
;             for (int n = 0; n < 2; ++n) {
;                 const int col = u.pn * 256 + bj * 128 + wc * 32 + n * 16 + fq * 4;
;                 f32x4 c1v = (f32x4){0.f, 0.f, 0.f, 0.f}, c2v = c1v;
;                 if (fold) { c1v = *(const f32x4*)(c1 + col); c2v = *(const f32x4*)(c2 + col); }
; #pragma unroll
;                 for (int ai = 0; ai < 2; ++ai)
; #pragma unroll
;                     for (int m = 0; m < 4; ++m) {
;                         f32x4 v = acc[ai][bj][m][n];
;                         if (fold) v = (v - c1v * mu[ai][m]) * rs[ai][m] + c2v;
;                         f(u.pm * 256 + ai * 128 + wr * 64 + m * 16 + fr, col, v, fq, ps1[ai][m], ps2[ai][m]);
;                     }
;     __device__ __forceinline__ void operator()(int row, int col, f32x4 v, int, float&, float&) const {
;         f32x4 r; r.x = fmaxf(v.x, 0.f); r.y = fmaxf(v.y, 0.f); r.z = fmaxf(v.z, 0.f); r.w = fmaxf(v.w, 0.f);
;         *(u32x2*)(O + (size_t)row * FF + col) = pk4(r * r);
;     }
	v_pk_fma_f32 v[42:43], v[150:151], v[42:43], v[38:39] op_sel_hi:[0,1,1]
	v_pk_fma_f32 v[40:41], v[150:151], v[40:41], v[36:37] op_sel_hi:[0,1,1]
	v_pk_fma_f32 v[34:35], v[154:155], v[34:35], v[38:39] op_sel_hi:[0,1,1]
	v_pk_fma_f32 v[32:33], v[154:155], v[32:33], v[36:37] op_sel_hi:[0,1,1]
	v_pk_fma_f32 v[26:27], v[158:159], v[26:27], v[38:39] op_sel_hi:[0,1,1]
	v_pk_fma_f32 v[24:25], v[158:159], v[24:25], v[36:37] op_sel_hi:[0,1,1]
	v_pk_fma_f32 v[22:23], v[190:191], v[22:23], v[38:39] op_sel_hi:[0,1,1]
	v_pk_fma_f32 v[20:21], v[190:191], v[20:21], v[36:37] op_sel_hi:[0,1,1]
	v_pk_fma_f32 v[18:19], v[188:189], v[18:19], v[38:39] op_sel_hi:[0,1,1]
	v_pk_fma_f32 v[16:17], v[188:189], v[16:17], v[36:37] op_sel_hi:[0,1,1]
	v_pk_fma_f32 v[14:15], v[186:187], v[14:15], v[38:39] op_sel_hi:[0,1,1]
	v_pk_fma_f32 v[12:13], v[186:187], v[12:13], v[36:37] op_sel_hi:[0,1,1]
	v_pk_fma_f32 v[10:11], v[182:183], v[10:11], v[38:39] op_sel_hi:[0,1,1]
	v_pk_fma_f32 v[8:9], v[182:183], v[8:9], v[36:37] op_sel_hi:[0,1,1]
	v_pk_fma_f32 v[6:7], v[166:167], v[6:7], v[38:39] op_sel_hi:[0,1,1]
	v_pk_fma_f32 v[4:5], v[166:167], v[4:5], v[36:37] op_sel_hi:[0,1,1]
	v_max_f32_e32 v40, 0, v40
	v_max_f32_e32 v41, 0, v41
	v_max_f32_e32 v42, 0, v42
	v_max_f32_e32 v43, 0, v43
	v_max_f32_e32 v32, 0, v32
	v_max_f32_e32 v33, 0, v33
	v_max_f32_e32 v34, 0, v34
	v_max_f32_e32 v35, 0, v35
	v_max_f32_e32 v24, 0, v24
	v_max_f32_e32 v25, 0, v25
	v_max_f32_e32 v26, 0, v26
	v_max_f32_e32 v27, 0, v27
	v_max_f32_e32 v20, 0, v20
	v_max_f32_e32 v21, 0, v21
	v_max_f32_e32 v22, 0, v22
	v_max_f32_e32 v23, 0, v23
	v_max_f32_e32 v16, 0, v16
	v_max_f32_e32 v17, 0, v17
	v_max_f32_e32 v18, 0, v18
	v_max_f32_e32 v19, 0, v19
	v_max_f32_e32 v12, 0, v12
	v_max_f32_e32 v13, 0, v13
	v_max_f32_e32 v14, 0, v14
	v_max_f32_e32 v15, 0, v15
	v_max_f32_e32 v8, 0, v8
	v_max_f32_e32 v9, 0, v9
	v_max_f32_e32 v10, 0, v10
	v_max_f32_e32 v11, 0, v11
	v_max_f32_e32 v4, 0, v4
	v_max_f32_e32 v5, 0, v5
	v_max_f32_e32 v6, 0, v6
	v_max_f32_e32 v7, 0, v7
	v_pk_mul_f32 v[42:43], v[42:43], v[42:43]
	v_pk_mul_f32 v[40:41], v[40:41], v[40:41]
	v_pk_mul_f32 v[34:35], v[34:35], v[34:35]
	v_pk_mul_f32 v[32:33], v[32:33], v[32:33]
	v_pk_mul_f32 v[26:27], v[26:27], v[26:27]
	v_pk_mul_f32 v[24:25], v[24:25], v[24:25]
	v_pk_mul_f32 v[22:23], v[22:23], v[22:23]
	v_pk_mul_f32 v[20:21], v[20:21], v[20:21]
	v_pk_mul_f32 v[18:19], v[18:19], v[18:19]
	v_pk_mul_f32 v[16:17], v[16:17], v[16:17]
	v_pk_mul_f32 v[14:15], v[14:15], v[14:15]
	v_pk_mul_f32 v[12:13], v[12:13], v[12:13]
	v_pk_mul_f32 v[10:11], v[10:11], v[10:11]
	v_pk_mul_f32 v[8:9], v[8:9], v[8:9]
	v_pk_mul_f32 v[6:7], v[6:7], v[6:7]
	v_pk_mul_f32 v[4:5], v[4:5], v[4:5]
	v_cvt_pk_bf16_f32 v40, v40, v41
	v_cvt_pk_bf16_f32 v41, v42, v43
	v_cvt_pk_bf16_f32 v32, v32, v33
	v_cvt_pk_bf16_f32 v33, v34, v35
	v_cvt_pk_bf16_f32 v24, v24, v25
	v_cvt_pk_bf16_f32 v25, v26, v27
	v_cvt_pk_bf16_f32 v20, v20, v21
	v_cvt_pk_bf16_f32 v21, v22, v23
	v_cvt_pk_bf16_f32 v16, v16, v17
	v_cvt_pk_bf16_f32 v17, v18, v19
	v_cvt_pk_bf16_f32 v12, v12, v13
	v_cvt_pk_bf16_f32 v13, v14, v15
	v_cvt_pk_bf16_f32 v8, v8, v9
	v_cvt_pk_bf16_f32 v9, v10, v11
	v_cvt_pk_bf16_f32 v4, v4, v5
	v_cvt_pk_bf16_f32 v5, v6, v7
	v_and_b32_e32 v148, 3, v219
	v_lshrrev_b32_e32 v149, 2, v219
	v_lshl_add_u32 v148, v148, 4, v149
	v_lshlrev_b32_e32 v148, 2, v148
	v_and_b32_e32 v152, 15, v219
	v_sub_u32_e32 v152, v149, v152
	v_lshlrev_b32_e32 v152, 13, v152
	v_and_b32_e32 v149, 3, v219
	v_lshrrev_b32_e32 v153, 4, v219
	v_sub_u32_e32 v149, v149, v153
	v_lshl_add_u32 v152, v149, 3, v152
	v_ashrrev_i32_e32 v153, 31, v152
	ds_bpermute_b32 v198, v148, v40
	ds_bpermute_b32 v199, v148, v41
	v_lshl_add_u64 v[180:181], v[152:153], 0, v[128:129]
	ds_bpermute_b32 v202, v148, v32
	ds_bpermute_b32 v203, v148, v33
	v_lshl_add_u64 v[200:201], v[152:153], 0, v[124:125]
	s_waitcnt lgkmcnt(0)
	global_store_dwordx2 v[180:181], v[198:199], off offset:288
	global_store_dwordx2 v[200:201], v[202:203], off offset:288
	ds_bpermute_b32 v198, v148, v24
	ds_bpermute_b32 v199, v148, v25
	v_lshl_add_u64 v[180:181], v[152:153], 0, v[120:121]
	ds_bpermute_b32 v202, v148, v20
	ds_bpermute_b32 v203, v148, v21
	v_lshl_add_u64 v[200:201], v[152:153], 0, v[116:117]
	s_waitcnt lgkmcnt(0)
	global_store_dwordx2 v[180:181], v[198:199], off offset:288
	global_store_dwordx2 v[200:201], v[202:203], off offset:288
	ds_bpermute_b32 v198, v148, v16
	ds_bpermute_b32 v199, v148, v17
	v_lshl_add_u64 v[180:181], v[152:153], 0, v[112:113]
	ds_bpermute_b32 v202, v148, v12
	ds_bpermute_b32 v203, v148, v13
	v_lshl_add_u64 v[200:201], v[152:153], 0, v[108:109]
	s_waitcnt lgkmcnt(0)
	global_store_dwordx2 v[180:181], v[198:199], off offset:288
	global_store_dwordx2 v[200:201], v[202:203], off offset:288
	ds_bpermute_b32 v198, v148, v8
	ds_bpermute_b32 v199, v148, v9
	v_lshl_add_u64 v[180:181], v[152:153], 0, v[100:101]
	ds_bpermute_b32 v202, v148, v4
	ds_bpermute_b32 v203, v148, v5
	v_lshl_add_u64 v[200:201], v[152:153], 0, v[92:93]
	s_waitcnt lgkmcnt(0)
	global_store_dwordx2 v[180:181], v[198:199], off offset:288
	global_store_dwordx2 v[200:201], v[202:203], off offset:288
	s_cbranch_vccnz .LBB0_2288
	s_and_b64 vcc, exec, s[38:39]
	s_cbranch_vccnz .LBB0_2287
	s_barrier
	s_branch .LBB0_2287
